# v24 plus back-edge rotation: the loop-carried pointer/counter SALU block of the five GEMM K-loops moved from after the closing barrier to before it (only the branch stays after)
# speedup vs baseline: 1.0297x; 1.0297x over previous
.LBB0_131:
	ds_read_b128 v[152:155], v145
	ds_read_b128 v[156:159], v145 offset:1024
	ds_read_b128 v[160:163], v145 offset:2048
	ds_read_b128 v[168:171], v145 offset:3072
	ds_read_b128 v[172:175], v146
	ds_read_b128 v[176:179], v146 offset:1024
	ds_read_b128 v[180:183], v146 offset:2048
	ds_read_b128 v[184:187], v146 offset:3072
	s_add_i32 s26, s24, 0xfdfc0080
	s_cmp_lg_u32 s34, 12
	s_cselect_b32 s26, s26, 0
	s_add_u32 s36, s8, s26
	s_addc_u32 s37, s9, 0
	s_add_u32 s26, s6, s26
	s_addc_u32 s27, s7, 0
	s_mov_b32 m0, s35
	v_lshl_add_u64 v[220:221], v[140:141], 0, s[24:25]
	ds_read_b128 v[188:191], v147
	ds_read_b128 v[192:195], v147 offset:1024
	ds_read_b128 v[196:199], v147 offset:2048
	ds_read_b128 v[200:203], v147 offset:3072
	ds_read_b128 v[204:207], v147 offset:4096
	ds_read_b128 v[208:211], v147 offset:5120
	ds_read_b128 v[212:215], v147 offset:6144
	ds_read_b128 v[216:219], v147 offset:7168
	global_load_lds_dwordx4 v[220:221], off
	v_lshl_add_u64 v[220:221], v[142:143], 0, s[24:25]
	s_mov_b32 m0, s38
	s_nop 0
	global_load_lds_dwordx4 v[220:221], off
	s_waitcnt vmcnt(8)
	s_waitcnt lgkmcnt(0)
	s_barrier
	s_setprio 1
	s_waitcnt lgkmcnt(0)
	v_mfma_f32_16x16x32_bf16 v[124:127], v[152:155], v[188:191], v[124:127]
	v_mfma_f32_16x16x32_bf16 v[120:123], v[160:163], v[188:191], v[120:123]
	v_mfma_f32_16x16x32_bf16 v[108:111], v[152:155], v[196:199], v[108:111]
	v_mfma_f32_16x16x32_bf16 v[104:107], v[160:163], v[196:199], v[104:107]
	v_mfma_f32_16x16x32_bf16 v[92:95], v[152:155], v[204:207], v[92:95]
	v_mfma_f32_16x16x32_bf16 v[88:91], v[160:163], v[204:207], v[88:91]
	v_mfma_f32_16x16x32_bf16 v[76:79], v[152:155], v[212:215], v[76:79]
	v_mfma_f32_16x16x32_bf16 v[72:75], v[160:163], v[212:215], v[72:75]
	v_mfma_f32_16x16x32_bf16 v[124:127], v[156:159], v[192:195], v[124:127]
	v_mfma_f32_16x16x32_bf16 v[120:123], v[168:171], v[192:195], v[120:123]
	v_mfma_f32_16x16x32_bf16 v[108:111], v[156:159], v[200:203], v[108:111]
	v_mfma_f32_16x16x32_bf16 v[104:107], v[168:171], v[200:203], v[104:107]
	v_mfma_f32_16x16x32_bf16 v[92:95], v[156:159], v[208:211], v[92:95]
	v_mfma_f32_16x16x32_bf16 v[88:91], v[168:171], v[208:211], v[88:91]
	v_mfma_f32_16x16x32_bf16 v[76:79], v[156:159], v[216:219], v[76:79]
	v_mfma_f32_16x16x32_bf16 v[72:75], v[168:171], v[216:219], v[72:75]
	v_mfma_f32_16x16x32_bf16 v[116:119], v[172:175], v[188:191], v[116:119]
	v_mfma_f32_16x16x32_bf16 v[112:115], v[180:183], v[188:191], v[112:115]
	v_mfma_f32_16x16x32_bf16 v[100:103], v[172:175], v[196:199], v[100:103]
	v_mfma_f32_16x16x32_bf16 v[96:99], v[180:183], v[196:199], v[96:99]
	v_mfma_f32_16x16x32_bf16 v[84:87], v[172:175], v[204:207], v[84:87]
	v_mfma_f32_16x16x32_bf16 v[80:83], v[180:183], v[204:207], v[80:83]
	v_mfma_f32_16x16x32_bf16 v[68:71], v[172:175], v[212:215], v[68:71]
	v_mfma_f32_16x16x32_bf16 v[64:67], v[180:183], v[212:215], v[64:67]
	v_mfma_f32_16x16x32_bf16 v[116:119], v[176:179], v[192:195], v[116:119]
	v_mfma_f32_16x16x32_bf16 v[112:115], v[184:187], v[192:195], v[112:115]
	v_mfma_f32_16x16x32_bf16 v[100:103], v[176:179], v[200:203], v[100:103]
	v_mfma_f32_16x16x32_bf16 v[96:99], v[184:187], v[200:203], v[96:99]
	v_mfma_f32_16x16x32_bf16 v[84:87], v[176:179], v[208:211], v[84:87]
	v_mfma_f32_16x16x32_bf16 v[80:83], v[184:187], v[208:211], v[80:83]
	v_mfma_f32_16x16x32_bf16 v[68:71], v[176:179], v[216:219], v[68:71]
	v_mfma_f32_16x16x32_bf16 v[64:67], v[184:187], v[216:219], v[64:67]
	s_setprio 0
	s_barrier
	s_mov_b32 m0, s39
	v_lshl_add_u64 v[220:221], s[26:27], 0, v[130:131]
	s_add_u32 s48, s26, 0x40000
	ds_read_b128 v[188:191], v147 offset:16384
	ds_read_b128 v[192:195], v147 offset:17408
	ds_read_b128 v[196:199], v147 offset:18432
	ds_read_b128 v[200:203], v147 offset:19456
	ds_read_b128 v[204:207], v147 offset:20480
	ds_read_b128 v[208:211], v147 offset:21504
	ds_read_b128 v[212:215], v147 offset:22528
	ds_read_b128 v[216:219], v147 offset:23552
	global_load_lds_dwordx4 v[220:221], off
	v_lshl_add_u64 v[222:223], s[26:27], 0, v[134:135]
	s_mov_b32 m0, s41
	s_addc_u32 s49, s27, 0
	global_load_lds_dwordx4 v[222:223], off
	v_lshl_add_u64 v[224:225], s[48:49], 0, v[130:131]
	s_mov_b32 m0, s42
	v_lshl_add_u64 v[226:227], s[36:37], 0, v[132:133]
	global_load_lds_dwordx4 v[224:225], off
	v_lshl_add_u64 v[224:225], s[48:49], 0, v[134:135]
	s_mov_b32 m0, s43
	s_nop 0
	global_load_lds_dwordx4 v[224:225], off
	v_lshl_add_u64 v[224:225], s[36:37], 0, v[128:129]
	s_mov_b32 m0, s3
	s_nop 0
	global_load_lds_dwordx4 v[224:225], off
	s_mov_b32 m0, s5
	s_nop 0
	global_load_lds_dwordx4 v[226:227], off
	s_waitcnt vmcnt(8)
	s_waitcnt lgkmcnt(0)
	s_barrier
	s_setprio 1
	s_waitcnt lgkmcnt(0)
	v_mfma_f32_16x16x32_bf16 v[60:63], v[152:155], v[188:191], v[60:63]
	v_mfma_f32_16x16x32_bf16 v[56:59], v[160:163], v[188:191], v[56:59]
	v_mfma_f32_16x16x32_bf16 v[44:47], v[152:155], v[196:199], v[44:47]
	v_mfma_f32_16x16x32_bf16 v[40:43], v[160:163], v[196:199], v[40:43]
	v_mfma_f32_16x16x32_bf16 v[28:31], v[152:155], v[204:207], v[28:31]
	v_mfma_f32_16x16x32_bf16 v[24:27], v[160:163], v[204:207], v[24:27]
	v_mfma_f32_16x16x32_bf16 v[12:15], v[152:155], v[212:215], v[12:15]
	v_mfma_f32_16x16x32_bf16 v[8:11], v[160:163], v[212:215], v[8:11]
	v_mfma_f32_16x16x32_bf16 v[60:63], v[156:159], v[192:195], v[60:63]
	v_mfma_f32_16x16x32_bf16 v[56:59], v[168:171], v[192:195], v[56:59]
	v_mfma_f32_16x16x32_bf16 v[44:47], v[156:159], v[200:203], v[44:47]
	v_mfma_f32_16x16x32_bf16 v[40:43], v[168:171], v[200:203], v[40:43]
	v_mfma_f32_16x16x32_bf16 v[28:31], v[156:159], v[208:211], v[28:31]
	v_mfma_f32_16x16x32_bf16 v[24:27], v[168:171], v[208:211], v[24:27]
	v_mfma_f32_16x16x32_bf16 v[12:15], v[156:159], v[216:219], v[12:15]
	v_mfma_f32_16x16x32_bf16 v[8:11], v[168:171], v[216:219], v[8:11]
	v_mfma_f32_16x16x32_bf16 v[52:55], v[172:175], v[188:191], v[52:55]
	v_mfma_f32_16x16x32_bf16 v[48:51], v[180:183], v[188:191], v[48:51]
	v_mfma_f32_16x16x32_bf16 v[36:39], v[172:175], v[196:199], v[36:39]
	v_mfma_f32_16x16x32_bf16 v[32:35], v[180:183], v[196:199], v[32:35]
	v_mfma_f32_16x16x32_bf16 v[20:23], v[172:175], v[204:207], v[20:23]
	v_mfma_f32_16x16x32_bf16 v[16:19], v[180:183], v[204:207], v[16:19]
	v_mfma_f32_16x16x32_bf16 v[4:7], v[172:175], v[212:215], v[4:7]
	v_mfma_f32_16x16x32_bf16 v[0:3], v[180:183], v[212:215], v[0:3]
	v_mfma_f32_16x16x32_bf16 v[52:55], v[176:179], v[192:195], v[52:55]
	v_mfma_f32_16x16x32_bf16 v[48:51], v[184:187], v[192:195], v[48:51]
	v_mfma_f32_16x16x32_bf16 v[36:39], v[176:179], v[200:203], v[36:39]
	v_mfma_f32_16x16x32_bf16 v[32:35], v[184:187], v[200:203], v[32:35]
	v_mfma_f32_16x16x32_bf16 v[20:23], v[176:179], v[208:211], v[20:23]
	v_mfma_f32_16x16x32_bf16 v[16:19], v[184:187], v[208:211], v[16:19]
	v_mfma_f32_16x16x32_bf16 v[4:7], v[176:179], v[216:219], v[4:7]
	v_mfma_f32_16x16x32_bf16 v[0:3], v[184:187], v[216:219], v[0:3]
	s_setprio 0
	s_barrier
	ds_read_b128 v[152:155], v148
	ds_read_b128 v[156:159], v148 offset:1024
	ds_read_b128 v[160:163], v148 offset:2048
	ds_read_b128 v[168:171], v148 offset:3072
	ds_read_b128 v[172:175], v150
	ds_read_b128 v[176:179], v150 offset:1024
	ds_read_b128 v[180:183], v150 offset:2048
	ds_read_b128 v[184:187], v150 offset:3072
	s_add_u32 s36, s36, 0x40000
	s_addc_u32 s37, s37, 0
	s_mov_b32 m0, s13
	v_lshl_add_u64 v[228:229], s[36:37], 0, v[128:129]
	ds_read_b128 v[188:191], v147 offset:32768
	ds_read_b128 v[192:195], v147 offset:33792
	ds_read_b128 v[196:199], v147 offset:34816
	ds_read_b128 v[200:203], v147 offset:35840
	ds_read_b128 v[204:207], v147 offset:36864
	ds_read_b128 v[208:211], v147 offset:37888
	ds_read_b128 v[212:215], v147 offset:38912
	ds_read_b128 v[216:219], v147 offset:39936
	global_load_lds_dwordx4 v[228:229], off
	v_lshl_add_u64 v[228:229], s[36:37], 0, v[132:133]
	s_mov_b32 m0, s15
	s_nop 0
	global_load_lds_dwordx4 v[228:229], off
	s_waitcnt vmcnt(8)
	s_waitcnt lgkmcnt(0)
	s_barrier
	s_setprio 1
	s_waitcnt lgkmcnt(0)
	v_mfma_f32_16x16x32_bf16 v[124:127], v[152:155], v[188:191], v[124:127]
	v_mfma_f32_16x16x32_bf16 v[120:123], v[160:163], v[188:191], v[120:123]
	v_mfma_f32_16x16x32_bf16 v[108:111], v[152:155], v[196:199], v[108:111]
	v_mfma_f32_16x16x32_bf16 v[104:107], v[160:163], v[196:199], v[104:107]
	v_mfma_f32_16x16x32_bf16 v[92:95], v[152:155], v[204:207], v[92:95]
	v_mfma_f32_16x16x32_bf16 v[88:91], v[160:163], v[204:207], v[88:91]
	v_mfma_f32_16x16x32_bf16 v[76:79], v[152:155], v[212:215], v[76:79]
	v_mfma_f32_16x16x32_bf16 v[72:75], v[160:163], v[212:215], v[72:75]
	v_mfma_f32_16x16x32_bf16 v[124:127], v[156:159], v[192:195], v[124:127]
	v_mfma_f32_16x16x32_bf16 v[120:123], v[168:171], v[192:195], v[120:123]
	v_mfma_f32_16x16x32_bf16 v[108:111], v[156:159], v[200:203], v[108:111]
	v_mfma_f32_16x16x32_bf16 v[104:107], v[168:171], v[200:203], v[104:107]
	v_mfma_f32_16x16x32_bf16 v[92:95], v[156:159], v[208:211], v[92:95]
	v_mfma_f32_16x16x32_bf16 v[88:91], v[168:171], v[208:211], v[88:91]
	v_mfma_f32_16x16x32_bf16 v[76:79], v[156:159], v[216:219], v[76:79]
	v_mfma_f32_16x16x32_bf16 v[72:75], v[168:171], v[216:219], v[72:75]
	v_mfma_f32_16x16x32_bf16 v[116:119], v[172:175], v[188:191], v[116:119]
	v_mfma_f32_16x16x32_bf16 v[112:115], v[180:183], v[188:191], v[112:115]
	v_mfma_f32_16x16x32_bf16 v[100:103], v[172:175], v[196:199], v[100:103]
	v_mfma_f32_16x16x32_bf16 v[96:99], v[180:183], v[196:199], v[96:99]
	v_mfma_f32_16x16x32_bf16 v[84:87], v[172:175], v[204:207], v[84:87]
	v_mfma_f32_16x16x32_bf16 v[80:83], v[180:183], v[204:207], v[80:83]
	v_mfma_f32_16x16x32_bf16 v[68:71], v[172:175], v[212:215], v[68:71]
	v_mfma_f32_16x16x32_bf16 v[64:67], v[180:183], v[212:215], v[64:67]
	v_mfma_f32_16x16x32_bf16 v[116:119], v[176:179], v[192:195], v[116:119]
	v_mfma_f32_16x16x32_bf16 v[112:115], v[184:187], v[192:195], v[112:115]
	v_mfma_f32_16x16x32_bf16 v[100:103], v[176:179], v[200:203], v[100:103]
	v_mfma_f32_16x16x32_bf16 v[96:99], v[184:187], v[200:203], v[96:99]
	v_mfma_f32_16x16x32_bf16 v[84:87], v[176:179], v[208:211], v[84:87]
	v_mfma_f32_16x16x32_bf16 v[80:83], v[184:187], v[208:211], v[80:83]
	v_mfma_f32_16x16x32_bf16 v[68:71], v[176:179], v[216:219], v[68:71]
	v_mfma_f32_16x16x32_bf16 v[64:67], v[184:187], v[216:219], v[64:67]
	s_setprio 0
	s_barrier
	s_mov_b32 m0, s44
	v_lshl_add_u64 v[220:221], v[220:221], 0, s[10:11]
	s_add_u32 s26, s26, 0x40080
	ds_read_b128 v[188:191], v147 offset:49152
	ds_read_b128 v[192:195], v147 offset:50176
	ds_read_b128 v[196:199], v147 offset:51200
	ds_read_b128 v[200:203], v147 offset:52224
	ds_read_b128 v[204:207], v147 offset:53248
	ds_read_b128 v[208:211], v147 offset:54272
	ds_read_b128 v[212:215], v147 offset:55296
	ds_read_b128 v[216:219], v147 offset:56320
	global_load_lds_dwordx4 v[220:221], off
	v_lshl_add_u64 v[220:221], v[222:223], 0, s[10:11]
	s_mov_b32 m0, s45
	s_addc_u32 s27, s27, 0
	global_load_lds_dwordx4 v[220:221], off
	v_lshl_add_u64 v[220:221], s[26:27], 0, v[130:131]
	s_mov_b32 m0, s46
	s_nop 0
	global_load_lds_dwordx4 v[220:221], off
	v_lshl_add_u64 v[220:221], s[26:27], 0, v[134:135]
	s_mov_b32 m0, s47
	s_nop 0
	global_load_lds_dwordx4 v[220:221], off
	v_lshl_add_u64 v[220:221], v[224:225], 0, s[10:11]
	s_mov_b32 m0, s19
	s_nop 0
	global_load_lds_dwordx4 v[220:221], off
	v_lshl_add_u64 v[220:221], v[226:227], 0, s[10:11]
	s_mov_b32 m0, s33
	s_nop 0
	global_load_lds_dwordx4 v[220:221], off
	s_waitcnt vmcnt(8)
	s_waitcnt lgkmcnt(0)
	s_barrier
	s_setprio 1
	s_waitcnt lgkmcnt(0)
	v_mfma_f32_16x16x32_bf16 v[60:63], v[152:155], v[188:191], v[60:63]
	v_mfma_f32_16x16x32_bf16 v[56:59], v[160:163], v[188:191], v[56:59]
	v_mfma_f32_16x16x32_bf16 v[44:47], v[152:155], v[196:199], v[44:47]
	v_mfma_f32_16x16x32_bf16 v[40:43], v[160:163], v[196:199], v[40:43]
	v_mfma_f32_16x16x32_bf16 v[28:31], v[152:155], v[204:207], v[28:31]
	v_mfma_f32_16x16x32_bf16 v[24:27], v[160:163], v[204:207], v[24:27]
	v_mfma_f32_16x16x32_bf16 v[12:15], v[152:155], v[212:215], v[12:15]
	v_mfma_f32_16x16x32_bf16 v[8:11], v[160:163], v[212:215], v[8:11]
	v_mfma_f32_16x16x32_bf16 v[60:63], v[156:159], v[192:195], v[60:63]
	v_mfma_f32_16x16x32_bf16 v[56:59], v[168:171], v[192:195], v[56:59]
	v_mfma_f32_16x16x32_bf16 v[44:47], v[156:159], v[200:203], v[44:47]
	v_mfma_f32_16x16x32_bf16 v[40:43], v[168:171], v[200:203], v[40:43]
	v_mfma_f32_16x16x32_bf16 v[28:31], v[156:159], v[208:211], v[28:31]
	v_mfma_f32_16x16x32_bf16 v[24:27], v[168:171], v[208:211], v[24:27]
	v_mfma_f32_16x16x32_bf16 v[12:15], v[156:159], v[216:219], v[12:15]
	v_mfma_f32_16x16x32_bf16 v[8:11], v[168:171], v[216:219], v[8:11]
	v_mfma_f32_16x16x32_bf16 v[52:55], v[172:175], v[188:191], v[52:55]
	v_mfma_f32_16x16x32_bf16 v[48:51], v[180:183], v[188:191], v[48:51]
	v_mfma_f32_16x16x32_bf16 v[36:39], v[172:175], v[196:199], v[36:39]
	v_mfma_f32_16x16x32_bf16 v[32:35], v[180:183], v[196:199], v[32:35]
	v_mfma_f32_16x16x32_bf16 v[20:23], v[172:175], v[204:207], v[20:23]
	v_mfma_f32_16x16x32_bf16 v[16:19], v[180:183], v[204:207], v[16:19]
	v_mfma_f32_16x16x32_bf16 v[4:7], v[172:175], v[212:215], v[4:7]
	v_mfma_f32_16x16x32_bf16 v[0:3], v[180:183], v[212:215], v[0:3]
	v_mfma_f32_16x16x32_bf16 v[52:55], v[176:179], v[192:195], v[52:55]
	v_mfma_f32_16x16x32_bf16 v[48:51], v[184:187], v[192:195], v[48:51]
	v_mfma_f32_16x16x32_bf16 v[36:39], v[176:179], v[200:203], v[36:39]
	v_mfma_f32_16x16x32_bf16 v[32:35], v[184:187], v[200:203], v[32:35]
	v_mfma_f32_16x16x32_bf16 v[20:23], v[176:179], v[208:211], v[20:23]
	v_mfma_f32_16x16x32_bf16 v[16:19], v[184:187], v[208:211], v[16:19]
	v_mfma_f32_16x16x32_bf16 v[4:7], v[176:179], v[216:219], v[4:7]
	v_mfma_f32_16x16x32_bf16 v[0:3], v[184:187], v[216:219], v[0:3]
	s_add_i32 s34, s34, 2
	s_add_u32 s24, s24, 0x100
	s_addc_u32 s25, s25, 0
	s_cmp_gt_u32 s34, 13
	s_setprio 0
	s_barrier
	s_cbranch_scc0 .LBB0_131
	s_cmpk_lt_u32 s2, 0x100
	s_cbranch_scc0 .LBB0_134
	s_barrier

.LBB0_681:
	ds_read_b128 v[128:131], v174
	ds_read_b128 v[132:135], v174 offset:1024
	ds_read_b128 v[160:163], v174 offset:2048
	ds_read_b128 v[178:181], v174 offset:3072
	ds_read_b128 v[182:185], v175
	ds_read_b128 v[186:189], v175 offset:1024
	ds_read_b128 v[190:193], v175 offset:2048
	ds_read_b128 v[194:197], v175 offset:3072
	s_add_u32 s10, s8, 0xfffc0080
	s_addc_u32 s11, s9, -1
	s_cmp_eq_u32 s48, 12
	s_cselect_b32 s13, s2, s11
	s_cselect_b32 s12, s7, s10
	s_cselect_b32 s11, s24, s42
	s_cselect_b32 s10, s33, s34
	v_lshl_add_u64 v[230:231], s[8:9], 0, v[152:153]
	s_add_i32 m0, s41, 0xc000
	ds_read_b128 v[198:201], v176
	ds_read_b128 v[202:205], v176 offset:1024
	ds_read_b128 v[206:209], v176 offset:2048
	ds_read_b128 v[210:213], v176 offset:3072
	ds_read_b128 v[214:217], v176 offset:4096
	ds_read_b128 v[218:221], v176 offset:5120
	ds_read_b128 v[222:225], v176 offset:6144
	ds_read_b128 v[226:229], v176 offset:7168
	global_load_lds_dwordx4 v[230:231], off
	v_lshl_add_u64 v[230:231], s[8:9], 0, v[154:155]
	s_add_i32 m0, s41, 0xe000
	s_nop 0
	global_load_lds_dwordx4 v[230:231], off
	s_waitcnt vmcnt(8)
	s_waitcnt lgkmcnt(0)
	s_barrier
	s_setprio 1
	s_waitcnt lgkmcnt(0)
	v_mfma_f32_16x16x32_bf16 v[124:127], v[128:131], v[198:201], v[124:127]
	v_mfma_f32_16x16x32_bf16 v[120:123], v[160:163], v[198:201], v[120:123]
	v_mfma_f32_16x16x32_bf16 v[108:111], v[128:131], v[206:209], v[108:111]
	v_mfma_f32_16x16x32_bf16 v[104:107], v[160:163], v[206:209], v[104:107]
	v_mfma_f32_16x16x32_bf16 v[92:95], v[128:131], v[214:217], v[92:95]
	v_mfma_f32_16x16x32_bf16 v[88:91], v[160:163], v[214:217], v[88:91]
	v_mfma_f32_16x16x32_bf16 v[76:79], v[128:131], v[222:225], v[76:79]
	v_mfma_f32_16x16x32_bf16 v[72:75], v[160:163], v[222:225], v[72:75]
	v_mfma_f32_16x16x32_bf16 v[124:127], v[132:135], v[202:205], v[124:127]
	v_mfma_f32_16x16x32_bf16 v[120:123], v[178:181], v[202:205], v[120:123]
	v_mfma_f32_16x16x32_bf16 v[108:111], v[132:135], v[210:213], v[108:111]
	v_mfma_f32_16x16x32_bf16 v[104:107], v[178:181], v[210:213], v[104:107]
	v_mfma_f32_16x16x32_bf16 v[92:95], v[132:135], v[218:221], v[92:95]
	v_mfma_f32_16x16x32_bf16 v[88:91], v[178:181], v[218:221], v[88:91]
	v_mfma_f32_16x16x32_bf16 v[76:79], v[132:135], v[226:229], v[76:79]
	v_mfma_f32_16x16x32_bf16 v[72:75], v[178:181], v[226:229], v[72:75]
	v_mfma_f32_16x16x32_bf16 v[116:119], v[182:185], v[198:201], v[116:119]
	v_mfma_f32_16x16x32_bf16 v[112:115], v[190:193], v[198:201], v[112:115]
	v_mfma_f32_16x16x32_bf16 v[100:103], v[182:185], v[206:209], v[100:103]
	v_mfma_f32_16x16x32_bf16 v[96:99], v[190:193], v[206:209], v[96:99]
	v_mfma_f32_16x16x32_bf16 v[84:87], v[182:185], v[214:217], v[84:87]
	v_mfma_f32_16x16x32_bf16 v[80:83], v[190:193], v[214:217], v[80:83]
	v_mfma_f32_16x16x32_bf16 v[68:71], v[182:185], v[222:225], v[68:71]
	v_mfma_f32_16x16x32_bf16 v[64:67], v[190:193], v[222:225], v[64:67]
	v_mfma_f32_16x16x32_bf16 v[116:119], v[186:189], v[202:205], v[116:119]
	v_mfma_f32_16x16x32_bf16 v[112:115], v[194:197], v[202:205], v[112:115]
	v_mfma_f32_16x16x32_bf16 v[100:103], v[186:189], v[210:213], v[100:103]
	v_mfma_f32_16x16x32_bf16 v[96:99], v[194:197], v[210:213], v[96:99]
	v_mfma_f32_16x16x32_bf16 v[84:87], v[186:189], v[218:221], v[84:87]
	v_mfma_f32_16x16x32_bf16 v[80:83], v[194:197], v[218:221], v[80:83]
	v_mfma_f32_16x16x32_bf16 v[68:71], v[186:189], v[226:229], v[68:71]
	v_mfma_f32_16x16x32_bf16 v[64:67], v[194:197], v[226:229], v[64:67]
	s_setprio 0
	s_barrier
	s_add_i32 s49, s94, s35
	v_lshl_add_u64 v[230:231], s[10:11], 0, v[142:143]
	s_mov_b32 m0, s49
	ds_read_b128 v[198:201], v176 offset:16384
	ds_read_b128 v[202:205], v176 offset:17408
	ds_read_b128 v[206:209], v176 offset:18432
	ds_read_b128 v[210:213], v176 offset:19456
	ds_read_b128 v[214:217], v176 offset:20480
	ds_read_b128 v[218:221], v176 offset:21504
	ds_read_b128 v[222:225], v176 offset:22528
	ds_read_b128 v[226:229], v176 offset:23552
	global_load_lds_dwordx4 v[230:231], off
	s_add_i32 m0, s49, 0x2000
	s_add_u32 s50, s10, 0x40000
	v_lshl_add_u64 v[232:233], s[10:11], 0, v[146:147]
	s_addc_u32 s51, s11, 0
	s_add_i32 s49, s95, s35
	global_load_lds_dwordx4 v[232:233], off
	v_lshl_add_u64 v[234:235], s[50:51], 0, v[142:143]
	s_mov_b32 m0, s49
	v_lshl_add_u64 v[236:237], s[12:13], 0, v[144:145]
	global_load_lds_dwordx4 v[234:235], off
	v_lshl_add_u64 v[234:235], s[50:51], 0, v[146:147]
	s_add_i32 m0, s49, 0x2000
	s_nop 0
	global_load_lds_dwordx4 v[234:235], off
	v_lshl_add_u64 v[234:235], s[12:13], 0, v[140:141]
	s_mov_b32 m0, s41
	s_nop 0
	global_load_lds_dwordx4 v[234:235], off
	s_mov_b32 m0, s55
	s_nop 0
	global_load_lds_dwordx4 v[236:237], off
	s_waitcnt vmcnt(8)
	s_waitcnt lgkmcnt(0)
	s_barrier
	s_setprio 1
	s_waitcnt lgkmcnt(0)
	v_mfma_f32_16x16x32_bf16 v[60:63], v[128:131], v[198:201], v[60:63]
	v_mfma_f32_16x16x32_bf16 v[56:59], v[160:163], v[198:201], v[56:59]
	v_mfma_f32_16x16x32_bf16 v[44:47], v[128:131], v[206:209], v[44:47]
	v_mfma_f32_16x16x32_bf16 v[40:43], v[160:163], v[206:209], v[40:43]
	v_mfma_f32_16x16x32_bf16 v[28:31], v[128:131], v[214:217], v[28:31]
	v_mfma_f32_16x16x32_bf16 v[24:27], v[160:163], v[214:217], v[24:27]
	v_mfma_f32_16x16x32_bf16 v[12:15], v[128:131], v[222:225], v[12:15]
	v_mfma_f32_16x16x32_bf16 v[8:11], v[160:163], v[222:225], v[8:11]
	v_mfma_f32_16x16x32_bf16 v[60:63], v[132:135], v[202:205], v[60:63]
	v_mfma_f32_16x16x32_bf16 v[56:59], v[178:181], v[202:205], v[56:59]
	v_mfma_f32_16x16x32_bf16 v[44:47], v[132:135], v[210:213], v[44:47]
	v_mfma_f32_16x16x32_bf16 v[40:43], v[178:181], v[210:213], v[40:43]
	v_mfma_f32_16x16x32_bf16 v[28:31], v[132:135], v[218:221], v[28:31]
	v_mfma_f32_16x16x32_bf16 v[24:27], v[178:181], v[218:221], v[24:27]
	v_mfma_f32_16x16x32_bf16 v[12:15], v[132:135], v[226:229], v[12:15]
	v_mfma_f32_16x16x32_bf16 v[8:11], v[178:181], v[226:229], v[8:11]
	v_mfma_f32_16x16x32_bf16 v[52:55], v[182:185], v[198:201], v[52:55]
	v_mfma_f32_16x16x32_bf16 v[48:51], v[190:193], v[198:201], v[48:51]
	v_mfma_f32_16x16x32_bf16 v[36:39], v[182:185], v[206:209], v[36:39]
	v_mfma_f32_16x16x32_bf16 v[32:35], v[190:193], v[206:209], v[32:35]
	v_mfma_f32_16x16x32_bf16 v[20:23], v[182:185], v[214:217], v[20:23]
	v_mfma_f32_16x16x32_bf16 v[16:19], v[190:193], v[214:217], v[16:19]
	v_mfma_f32_16x16x32_bf16 v[4:7], v[182:185], v[222:225], v[4:7]
	v_mfma_f32_16x16x32_bf16 v[0:3], v[190:193], v[222:225], v[0:3]
	v_mfma_f32_16x16x32_bf16 v[52:55], v[186:189], v[202:205], v[52:55]
	v_mfma_f32_16x16x32_bf16 v[48:51], v[194:197], v[202:205], v[48:51]
	v_mfma_f32_16x16x32_bf16 v[36:39], v[186:189], v[210:213], v[36:39]
	v_mfma_f32_16x16x32_bf16 v[32:35], v[194:197], v[210:213], v[32:35]
	v_mfma_f32_16x16x32_bf16 v[20:23], v[186:189], v[218:221], v[20:23]
	v_mfma_f32_16x16x32_bf16 v[16:19], v[194:197], v[218:221], v[16:19]
	v_mfma_f32_16x16x32_bf16 v[4:7], v[186:189], v[226:229], v[4:7]
	v_mfma_f32_16x16x32_bf16 v[0:3], v[194:197], v[226:229], v[0:3]
	s_setprio 0
	s_barrier
	s_add_i32 s49, 0, 0x18000
	v_add_u32_e32 v148, s49, v167
	s_add_i32 s50, 0, 0x1c000
	ds_read_b128 v[128:131], v148
	ds_read_b128 v[132:135], v148 offset:1024
	ds_read_b128 v[160:163], v148 offset:2048
	ds_read_b128 v[178:181], v148 offset:3072
	v_add_u32_e32 v148, s50, v167
	ds_read_b128 v[182:185], v148
	ds_read_b128 v[186:189], v148 offset:1024
	ds_read_b128 v[190:193], v148 offset:2048
	ds_read_b128 v[194:197], v148 offset:3072
	s_add_u32 s12, s12, 0x40000
	s_addc_u32 s13, s13, 0
	s_mov_b32 m0, s59
	v_lshl_add_u64 v[238:239], s[12:13], 0, v[140:141]
	ds_read_b128 v[198:201], v176 offset:32768
	ds_read_b128 v[202:205], v176 offset:33792
	ds_read_b128 v[206:209], v176 offset:34816
	ds_read_b128 v[210:213], v176 offset:35840
	ds_read_b128 v[214:217], v176 offset:36864
	ds_read_b128 v[218:221], v176 offset:37888
	ds_read_b128 v[222:225], v176 offset:38912
	ds_read_b128 v[226:229], v176 offset:39936
	global_load_lds_dwordx4 v[238:239], off
	v_lshl_add_u64 v[238:239], s[12:13], 0, v[144:145]
	s_mov_b32 m0, s61
	s_nop 0
	global_load_lds_dwordx4 v[238:239], off
	s_waitcnt vmcnt(8)
	s_waitcnt lgkmcnt(0)
	s_barrier
	s_setprio 1
	s_waitcnt lgkmcnt(0)
	v_mfma_f32_16x16x32_bf16 v[124:127], v[128:131], v[198:201], v[124:127]
	v_mfma_f32_16x16x32_bf16 v[120:123], v[160:163], v[198:201], v[120:123]
	v_mfma_f32_16x16x32_bf16 v[108:111], v[128:131], v[206:209], v[108:111]
	v_mfma_f32_16x16x32_bf16 v[104:107], v[160:163], v[206:209], v[104:107]
	v_mfma_f32_16x16x32_bf16 v[92:95], v[128:131], v[214:217], v[92:95]
	v_mfma_f32_16x16x32_bf16 v[88:91], v[160:163], v[214:217], v[88:91]
	v_mfma_f32_16x16x32_bf16 v[76:79], v[128:131], v[222:225], v[76:79]
	v_mfma_f32_16x16x32_bf16 v[72:75], v[160:163], v[222:225], v[72:75]
	v_mfma_f32_16x16x32_bf16 v[124:127], v[132:135], v[202:205], v[124:127]
	v_mfma_f32_16x16x32_bf16 v[120:123], v[178:181], v[202:205], v[120:123]
	v_mfma_f32_16x16x32_bf16 v[108:111], v[132:135], v[210:213], v[108:111]
	v_mfma_f32_16x16x32_bf16 v[104:107], v[178:181], v[210:213], v[104:107]
	v_mfma_f32_16x16x32_bf16 v[92:95], v[132:135], v[218:221], v[92:95]
	v_mfma_f32_16x16x32_bf16 v[88:91], v[178:181], v[218:221], v[88:91]
	v_mfma_f32_16x16x32_bf16 v[76:79], v[132:135], v[226:229], v[76:79]
	v_mfma_f32_16x16x32_bf16 v[72:75], v[178:181], v[226:229], v[72:75]
	v_mfma_f32_16x16x32_bf16 v[116:119], v[182:185], v[198:201], v[116:119]
	v_mfma_f32_16x16x32_bf16 v[112:115], v[190:193], v[198:201], v[112:115]
	v_mfma_f32_16x16x32_bf16 v[100:103], v[182:185], v[206:209], v[100:103]
	v_mfma_f32_16x16x32_bf16 v[96:99], v[190:193], v[206:209], v[96:99]
	v_mfma_f32_16x16x32_bf16 v[84:87], v[182:185], v[214:217], v[84:87]
	v_mfma_f32_16x16x32_bf16 v[80:83], v[190:193], v[214:217], v[80:83]
	v_mfma_f32_16x16x32_bf16 v[68:71], v[182:185], v[222:225], v[68:71]
	v_mfma_f32_16x16x32_bf16 v[64:67], v[190:193], v[222:225], v[64:67]
	v_mfma_f32_16x16x32_bf16 v[116:119], v[186:189], v[202:205], v[116:119]
	v_mfma_f32_16x16x32_bf16 v[112:115], v[194:197], v[202:205], v[112:115]
	v_mfma_f32_16x16x32_bf16 v[100:103], v[186:189], v[210:213], v[100:103]
	v_mfma_f32_16x16x32_bf16 v[96:99], v[194:197], v[210:213], v[96:99]
	v_mfma_f32_16x16x32_bf16 v[84:87], v[186:189], v[218:221], v[84:87]
	v_mfma_f32_16x16x32_bf16 v[80:83], v[194:197], v[218:221], v[80:83]
	v_mfma_f32_16x16x32_bf16 v[68:71], v[186:189], v[226:229], v[68:71]
	v_mfma_f32_16x16x32_bf16 v[64:67], v[194:197], v[226:229], v[64:67]
	s_setprio 0
	s_barrier
	s_add_i32 s12, s49, s35
	v_lshl_add_u64 v[230:231], v[230:231], 0, s[36:37]
	s_mov_b32 m0, s12
	ds_read_b128 v[198:201], v176 offset:49152
	ds_read_b128 v[202:205], v176 offset:50176
	ds_read_b128 v[206:209], v176 offset:51200
	ds_read_b128 v[210:213], v176 offset:52224
	ds_read_b128 v[214:217], v176 offset:53248
	ds_read_b128 v[218:221], v176 offset:54272
	ds_read_b128 v[222:225], v176 offset:55296
	ds_read_b128 v[226:229], v176 offset:56320
	global_load_lds_dwordx4 v[230:231], off
	s_add_i32 m0, s12, 0x2000
	s_add_u32 s10, s10, 0x40080
	v_lshl_add_u64 v[230:231], v[232:233], 0, s[36:37]
	s_addc_u32 s11, s11, 0
	s_add_i32 s12, s50, s35
	global_load_lds_dwordx4 v[230:231], off
	v_lshl_add_u64 v[230:231], s[10:11], 0, v[142:143]
	s_mov_b32 m0, s12
	s_nop 0
	global_load_lds_dwordx4 v[230:231], off
	v_lshl_add_u64 v[230:231], s[10:11], 0, v[146:147]
	s_add_i32 m0, s12, 0x2000
	s_nop 0
	global_load_lds_dwordx4 v[230:231], off
	v_lshl_add_u64 v[230:231], v[234:235], 0, s[36:37]
	s_mov_b32 m0, s82
	s_nop 0
	global_load_lds_dwordx4 v[230:231], off
	v_lshl_add_u64 v[230:231], v[236:237], 0, s[36:37]
	s_mov_b32 m0, s83
	s_nop 0
	global_load_lds_dwordx4 v[230:231], off
	s_waitcnt vmcnt(8)
	s_waitcnt lgkmcnt(0)
	s_barrier
	s_setprio 1
	s_waitcnt lgkmcnt(0)
	v_mfma_f32_16x16x32_bf16 v[60:63], v[128:131], v[198:201], v[60:63]
	v_mfma_f32_16x16x32_bf16 v[56:59], v[160:163], v[198:201], v[56:59]
	v_mfma_f32_16x16x32_bf16 v[44:47], v[128:131], v[206:209], v[44:47]
	v_mfma_f32_16x16x32_bf16 v[40:43], v[160:163], v[206:209], v[40:43]
	v_mfma_f32_16x16x32_bf16 v[28:31], v[128:131], v[214:217], v[28:31]
	v_mfma_f32_16x16x32_bf16 v[24:27], v[160:163], v[214:217], v[24:27]
	v_mfma_f32_16x16x32_bf16 v[12:15], v[128:131], v[222:225], v[12:15]
	v_mfma_f32_16x16x32_bf16 v[8:11], v[160:163], v[222:225], v[8:11]
	v_mfma_f32_16x16x32_bf16 v[60:63], v[132:135], v[202:205], v[60:63]
	v_mfma_f32_16x16x32_bf16 v[56:59], v[178:181], v[202:205], v[56:59]
	v_mfma_f32_16x16x32_bf16 v[44:47], v[132:135], v[210:213], v[44:47]
	v_mfma_f32_16x16x32_bf16 v[40:43], v[178:181], v[210:213], v[40:43]
	v_mfma_f32_16x16x32_bf16 v[28:31], v[132:135], v[218:221], v[28:31]
	v_mfma_f32_16x16x32_bf16 v[24:27], v[178:181], v[218:221], v[24:27]
	v_mfma_f32_16x16x32_bf16 v[12:15], v[132:135], v[226:229], v[12:15]
	v_mfma_f32_16x16x32_bf16 v[8:11], v[178:181], v[226:229], v[8:11]
	v_mfma_f32_16x16x32_bf16 v[52:55], v[182:185], v[198:201], v[52:55]
	v_mfma_f32_16x16x32_bf16 v[48:51], v[190:193], v[198:201], v[48:51]
	v_mfma_f32_16x16x32_bf16 v[36:39], v[182:185], v[206:209], v[36:39]
	v_mfma_f32_16x16x32_bf16 v[32:35], v[190:193], v[206:209], v[32:35]
	v_mfma_f32_16x16x32_bf16 v[20:23], v[182:185], v[214:217], v[20:23]
	v_mfma_f32_16x16x32_bf16 v[16:19], v[190:193], v[214:217], v[16:19]
	v_mfma_f32_16x16x32_bf16 v[4:7], v[182:185], v[222:225], v[4:7]
	v_mfma_f32_16x16x32_bf16 v[0:3], v[190:193], v[222:225], v[0:3]
	v_mfma_f32_16x16x32_bf16 v[52:55], v[186:189], v[202:205], v[52:55]
	v_mfma_f32_16x16x32_bf16 v[48:51], v[194:197], v[202:205], v[48:51]
	v_mfma_f32_16x16x32_bf16 v[36:39], v[186:189], v[210:213], v[36:39]
	v_mfma_f32_16x16x32_bf16 v[32:35], v[194:197], v[210:213], v[32:35]
	v_mfma_f32_16x16x32_bf16 v[20:23], v[186:189], v[218:221], v[20:23]
	v_mfma_f32_16x16x32_bf16 v[16:19], v[194:197], v[218:221], v[16:19]
	v_mfma_f32_16x16x32_bf16 v[4:7], v[186:189], v[226:229], v[4:7]
	v_mfma_f32_16x16x32_bf16 v[0:3], v[194:197], v[226:229], v[0:3]
	s_add_i32 s48, s48, 2
	s_add_u32 s8, s8, 0x100
	s_addc_u32 s9, s9, 0
	s_add_u32 s34, s34, 0x100
	s_addc_u32 s42, s42, 0
	s_cmp_gt_u32 s48, 13
	s_setprio 0
	s_barrier
	s_cbranch_scc0 .LBB0_681
	s_and_b64 vcc, exec, s[38:39]
	s_cbranch_vccz .LBB0_684
	s_barrier

.LBB0_1506:
	ds_read_b128 v[166:169], v159
	ds_read_b128 v[170:173], v159 offset:1024
	ds_read_b128 v[174:177], v159 offset:2048
	ds_read_b128 v[178:181], v159 offset:3072
	ds_read_b128 v[182:185], v160
	ds_read_b128 v[186:189], v160 offset:1024
	ds_read_b128 v[190:193], v160 offset:2048
	ds_read_b128 v[194:197], v160 offset:3072
	s_add_i32 s49, s48, 2
	s_add_u32 s50, s68, 0xfffc0080
	s_addc_u32 s51, s69, -1
	s_cmp_eq_u32 s33, s48
	s_cselect_b32 s73, s61, s51
	s_cselect_b32 s72, s60, s50
	s_cselect_b32 s71, s63, s42
	s_cselect_b32 s70, s62, s34
	v_lshl_add_u64 v[146:147], s[68:69], 0, v[142:143]
	s_add_i32 m0, s14, 0xc000
	ds_read_b128 v[198:201], v161
	ds_read_b128 v[202:205], v161 offset:1024
	ds_read_b128 v[206:209], v161 offset:2048
	ds_read_b128 v[210:213], v161 offset:3072
	ds_read_b128 v[214:217], v161 offset:4096
	ds_read_b128 v[218:221], v161 offset:5120
	ds_read_b128 v[222:225], v161 offset:6144
	ds_read_b128 v[226:229], v161 offset:7168
	global_load_lds_dwordx4 v[146:147], off
	v_lshl_add_u64 v[146:147], s[68:69], 0, v[144:145]
	s_add_i32 m0, s14, 0xe000
	s_nop 0
	global_load_lds_dwordx4 v[146:147], off
	s_waitcnt vmcnt(8)
	s_waitcnt lgkmcnt(0)
	s_barrier
	s_setprio 1
	s_waitcnt lgkmcnt(0)
	v_mfma_f32_16x16x32_bf16 v[124:127], v[166:169], v[198:201], v[124:127]
	v_mfma_f32_16x16x32_bf16 v[120:123], v[174:177], v[198:201], v[120:123]
	v_mfma_f32_16x16x32_bf16 v[108:111], v[166:169], v[206:209], v[108:111]
	v_mfma_f32_16x16x32_bf16 v[104:107], v[174:177], v[206:209], v[104:107]
	v_mfma_f32_16x16x32_bf16 v[92:95], v[166:169], v[214:217], v[92:95]
	v_mfma_f32_16x16x32_bf16 v[88:91], v[174:177], v[214:217], v[88:91]
	v_mfma_f32_16x16x32_bf16 v[76:79], v[166:169], v[222:225], v[76:79]
	v_mfma_f32_16x16x32_bf16 v[72:75], v[174:177], v[222:225], v[72:75]
	v_mfma_f32_16x16x32_bf16 v[124:127], v[170:173], v[202:205], v[124:127]
	v_mfma_f32_16x16x32_bf16 v[120:123], v[178:181], v[202:205], v[120:123]
	v_mfma_f32_16x16x32_bf16 v[108:111], v[170:173], v[210:213], v[108:111]
	v_mfma_f32_16x16x32_bf16 v[104:107], v[178:181], v[210:213], v[104:107]
	v_mfma_f32_16x16x32_bf16 v[92:95], v[170:173], v[218:221], v[92:95]
	v_mfma_f32_16x16x32_bf16 v[88:91], v[178:181], v[218:221], v[88:91]
	v_mfma_f32_16x16x32_bf16 v[76:79], v[170:173], v[226:229], v[76:79]
	v_mfma_f32_16x16x32_bf16 v[72:75], v[178:181], v[226:229], v[72:75]
	v_mfma_f32_16x16x32_bf16 v[116:119], v[182:185], v[198:201], v[116:119]
	v_mfma_f32_16x16x32_bf16 v[112:115], v[190:193], v[198:201], v[112:115]
	v_mfma_f32_16x16x32_bf16 v[100:103], v[182:185], v[206:209], v[100:103]
	v_mfma_f32_16x16x32_bf16 v[96:99], v[190:193], v[206:209], v[96:99]
	v_mfma_f32_16x16x32_bf16 v[84:87], v[182:185], v[214:217], v[84:87]
	v_mfma_f32_16x16x32_bf16 v[80:83], v[190:193], v[214:217], v[80:83]
	v_mfma_f32_16x16x32_bf16 v[68:71], v[182:185], v[222:225], v[68:71]
	v_mfma_f32_16x16x32_bf16 v[64:67], v[190:193], v[222:225], v[64:67]
	v_mfma_f32_16x16x32_bf16 v[116:119], v[186:189], v[202:205], v[116:119]
	v_mfma_f32_16x16x32_bf16 v[112:115], v[194:197], v[202:205], v[112:115]
	v_mfma_f32_16x16x32_bf16 v[100:103], v[186:189], v[210:213], v[100:103]
	v_mfma_f32_16x16x32_bf16 v[96:99], v[194:197], v[210:213], v[96:99]
	v_mfma_f32_16x16x32_bf16 v[84:87], v[186:189], v[218:221], v[84:87]
	v_mfma_f32_16x16x32_bf16 v[80:83], v[194:197], v[218:221], v[80:83]
	v_mfma_f32_16x16x32_bf16 v[68:71], v[186:189], v[226:229], v[68:71]
	v_mfma_f32_16x16x32_bf16 v[64:67], v[194:197], v[226:229], v[64:67]
	s_setprio 0
	s_barrier
	s_add_i32 s48, s52, s3
	v_lshl_add_u64 v[146:147], s[70:71], 0, v[132:133]
	s_mov_b32 m0, s48
	ds_read_b128 v[198:201], v161 offset:16384
	ds_read_b128 v[202:205], v161 offset:17408
	ds_read_b128 v[206:209], v161 offset:18432
	ds_read_b128 v[210:213], v161 offset:19456
	ds_read_b128 v[214:217], v161 offset:20480
	ds_read_b128 v[218:221], v161 offset:21504
	ds_read_b128 v[222:225], v161 offset:22528
	ds_read_b128 v[226:229], v161 offset:23552
	global_load_lds_dwordx4 v[146:147], off
	s_add_i32 m0, s48, 0x2000
	s_add_u32 s50, s70, 0x40000
	v_lshl_add_u64 v[162:163], s[70:71], 0, v[136:137]
	s_addc_u32 s51, s71, 0
	s_add_i32 s48, s53, s3
	global_load_lds_dwordx4 v[162:163], off
	v_lshl_add_u64 v[230:231], s[50:51], 0, v[132:133]
	s_mov_b32 m0, s48
	v_lshl_add_u64 v[232:233], s[72:73], 0, v[134:135]
	global_load_lds_dwordx4 v[230:231], off
	v_lshl_add_u64 v[230:231], s[50:51], 0, v[136:137]
	s_add_i32 m0, s48, 0x2000
	s_nop 0
	global_load_lds_dwordx4 v[230:231], off
	v_lshl_add_u64 v[230:231], s[72:73], 0, v[130:131]
	s_mov_b32 m0, s14
	s_nop 0
	global_load_lds_dwordx4 v[230:231], off
	s_mov_b32 m0, s15
	s_nop 0
	global_load_lds_dwordx4 v[232:233], off
	s_waitcnt vmcnt(8)
	s_waitcnt lgkmcnt(0)
	s_barrier
	s_setprio 1
	s_waitcnt lgkmcnt(0)
	v_mfma_f32_16x16x32_bf16 v[60:63], v[166:169], v[198:201], v[60:63]
	v_mfma_f32_16x16x32_bf16 v[56:59], v[174:177], v[198:201], v[56:59]
	v_mfma_f32_16x16x32_bf16 v[44:47], v[166:169], v[206:209], v[44:47]
	v_mfma_f32_16x16x32_bf16 v[40:43], v[174:177], v[206:209], v[40:43]
	v_mfma_f32_16x16x32_bf16 v[28:31], v[166:169], v[214:217], v[28:31]
	v_mfma_f32_16x16x32_bf16 v[24:27], v[174:177], v[214:217], v[24:27]
	v_mfma_f32_16x16x32_bf16 v[12:15], v[166:169], v[222:225], v[12:15]
	v_mfma_f32_16x16x32_bf16 v[8:11], v[174:177], v[222:225], v[8:11]
	v_mfma_f32_16x16x32_bf16 v[60:63], v[170:173], v[202:205], v[60:63]
	v_mfma_f32_16x16x32_bf16 v[56:59], v[178:181], v[202:205], v[56:59]
	v_mfma_f32_16x16x32_bf16 v[44:47], v[170:173], v[210:213], v[44:47]
	v_mfma_f32_16x16x32_bf16 v[40:43], v[178:181], v[210:213], v[40:43]
	v_mfma_f32_16x16x32_bf16 v[28:31], v[170:173], v[218:221], v[28:31]
	v_mfma_f32_16x16x32_bf16 v[24:27], v[178:181], v[218:221], v[24:27]
	v_mfma_f32_16x16x32_bf16 v[12:15], v[170:173], v[226:229], v[12:15]
	v_mfma_f32_16x16x32_bf16 v[8:11], v[178:181], v[226:229], v[8:11]
	v_mfma_f32_16x16x32_bf16 v[52:55], v[182:185], v[198:201], v[52:55]
	v_mfma_f32_16x16x32_bf16 v[48:51], v[190:193], v[198:201], v[48:51]
	v_mfma_f32_16x16x32_bf16 v[36:39], v[182:185], v[206:209], v[36:39]
	v_mfma_f32_16x16x32_bf16 v[32:35], v[190:193], v[206:209], v[32:35]
	v_mfma_f32_16x16x32_bf16 v[20:23], v[182:185], v[214:217], v[20:23]
	v_mfma_f32_16x16x32_bf16 v[16:19], v[190:193], v[214:217], v[16:19]
	v_mfma_f32_16x16x32_bf16 v[4:7], v[182:185], v[222:225], v[4:7]
	v_mfma_f32_16x16x32_bf16 v[0:3], v[190:193], v[222:225], v[0:3]
	v_mfma_f32_16x16x32_bf16 v[52:55], v[186:189], v[202:205], v[52:55]
	v_mfma_f32_16x16x32_bf16 v[48:51], v[194:197], v[202:205], v[48:51]
	v_mfma_f32_16x16x32_bf16 v[36:39], v[186:189], v[210:213], v[36:39]
	v_mfma_f32_16x16x32_bf16 v[32:35], v[194:197], v[210:213], v[32:35]
	v_mfma_f32_16x16x32_bf16 v[20:23], v[186:189], v[218:221], v[20:23]
	v_mfma_f32_16x16x32_bf16 v[16:19], v[194:197], v[218:221], v[16:19]
	v_mfma_f32_16x16x32_bf16 v[4:7], v[186:189], v[226:229], v[4:7]
	v_mfma_f32_16x16x32_bf16 v[0:3], v[194:197], v[226:229], v[0:3]
	s_setprio 0
	s_barrier
	s_add_i32 s48, 0, 0x18000
	v_add_u32_e32 v138, s48, v141
	s_add_i32 s55, 0, 0x1c000
	ds_read_b128 v[166:169], v138
	ds_read_b128 v[170:173], v138 offset:1024
	ds_read_b128 v[174:177], v138 offset:2048
	ds_read_b128 v[178:181], v138 offset:3072
	v_add_u32_e32 v138, s55, v141
	ds_read_b128 v[182:185], v138
	ds_read_b128 v[186:189], v138 offset:1024
	ds_read_b128 v[190:193], v138 offset:2048
	ds_read_b128 v[194:197], v138 offset:3072
	s_add_u32 s50, s72, 0x40000
	s_addc_u32 s51, s73, 0
	s_mov_b32 m0, s18
	v_lshl_add_u64 v[234:235], s[50:51], 0, v[130:131]
	ds_read_b128 v[198:201], v161 offset:32768
	ds_read_b128 v[202:205], v161 offset:33792
	ds_read_b128 v[206:209], v161 offset:34816
	ds_read_b128 v[210:213], v161 offset:35840
	ds_read_b128 v[214:217], v161 offset:36864
	ds_read_b128 v[218:221], v161 offset:37888
	ds_read_b128 v[222:225], v161 offset:38912
	ds_read_b128 v[226:229], v161 offset:39936
	global_load_lds_dwordx4 v[234:235], off
	v_lshl_add_u64 v[234:235], s[50:51], 0, v[134:135]
	s_mov_b32 m0, s19
	s_nop 0
	global_load_lds_dwordx4 v[234:235], off
	s_waitcnt vmcnt(8)
	s_waitcnt lgkmcnt(0)
	s_barrier
	s_setprio 1
	s_waitcnt lgkmcnt(0)
	v_mfma_f32_16x16x32_bf16 v[124:127], v[166:169], v[198:201], v[124:127]
	v_mfma_f32_16x16x32_bf16 v[120:123], v[174:177], v[198:201], v[120:123]
	v_mfma_f32_16x16x32_bf16 v[108:111], v[166:169], v[206:209], v[108:111]
	v_mfma_f32_16x16x32_bf16 v[104:107], v[174:177], v[206:209], v[104:107]
	v_mfma_f32_16x16x32_bf16 v[92:95], v[166:169], v[214:217], v[92:95]
	v_mfma_f32_16x16x32_bf16 v[88:91], v[174:177], v[214:217], v[88:91]
	v_mfma_f32_16x16x32_bf16 v[76:79], v[166:169], v[222:225], v[76:79]
	v_mfma_f32_16x16x32_bf16 v[72:75], v[174:177], v[222:225], v[72:75]
	v_mfma_f32_16x16x32_bf16 v[124:127], v[170:173], v[202:205], v[124:127]
	v_mfma_f32_16x16x32_bf16 v[120:123], v[178:181], v[202:205], v[120:123]
	v_mfma_f32_16x16x32_bf16 v[108:111], v[170:173], v[210:213], v[108:111]
	v_mfma_f32_16x16x32_bf16 v[104:107], v[178:181], v[210:213], v[104:107]
	v_mfma_f32_16x16x32_bf16 v[92:95], v[170:173], v[218:221], v[92:95]
	v_mfma_f32_16x16x32_bf16 v[88:91], v[178:181], v[218:221], v[88:91]
	v_mfma_f32_16x16x32_bf16 v[76:79], v[170:173], v[226:229], v[76:79]
	v_mfma_f32_16x16x32_bf16 v[72:75], v[178:181], v[226:229], v[72:75]
	v_mfma_f32_16x16x32_bf16 v[116:119], v[182:185], v[198:201], v[116:119]
	v_mfma_f32_16x16x32_bf16 v[112:115], v[190:193], v[198:201], v[112:115]
	v_mfma_f32_16x16x32_bf16 v[100:103], v[182:185], v[206:209], v[100:103]
	v_mfma_f32_16x16x32_bf16 v[96:99], v[190:193], v[206:209], v[96:99]
	v_mfma_f32_16x16x32_bf16 v[84:87], v[182:185], v[214:217], v[84:87]
	v_mfma_f32_16x16x32_bf16 v[80:83], v[190:193], v[214:217], v[80:83]
	v_mfma_f32_16x16x32_bf16 v[68:71], v[182:185], v[222:225], v[68:71]
	v_mfma_f32_16x16x32_bf16 v[64:67], v[190:193], v[222:225], v[64:67]
	v_mfma_f32_16x16x32_bf16 v[116:119], v[186:189], v[202:205], v[116:119]
	v_mfma_f32_16x16x32_bf16 v[112:115], v[194:197], v[202:205], v[112:115]
	v_mfma_f32_16x16x32_bf16 v[100:103], v[186:189], v[210:213], v[100:103]
	v_mfma_f32_16x16x32_bf16 v[96:99], v[194:197], v[210:213], v[96:99]
	v_mfma_f32_16x16x32_bf16 v[84:87], v[186:189], v[218:221], v[84:87]
	v_mfma_f32_16x16x32_bf16 v[80:83], v[194:197], v[218:221], v[80:83]
	v_mfma_f32_16x16x32_bf16 v[68:71], v[186:189], v[226:229], v[68:71]
	v_mfma_f32_16x16x32_bf16 v[64:67], v[194:197], v[226:229], v[64:67]
	s_setprio 0
	s_barrier
	s_add_i32 s48, s48, s3
	v_lshl_add_u64 v[146:147], v[146:147], 0, s[26:27]
	s_mov_b32 m0, s48
	ds_read_b128 v[198:201], v161 offset:49152
	ds_read_b128 v[202:205], v161 offset:50176
	ds_read_b128 v[206:209], v161 offset:51200
	ds_read_b128 v[210:213], v161 offset:52224
	ds_read_b128 v[214:217], v161 offset:53248
	ds_read_b128 v[218:221], v161 offset:54272
	ds_read_b128 v[222:225], v161 offset:55296
	ds_read_b128 v[226:229], v161 offset:56320
	global_load_lds_dwordx4 v[146:147], off
	s_add_i32 m0, s48, 0x2000
	s_add_u32 s50, s70, 0x40080
	v_lshl_add_u64 v[146:147], v[162:163], 0, s[26:27]
	s_addc_u32 s51, s71, 0
	s_add_i32 s48, s55, s3
	global_load_lds_dwordx4 v[146:147], off
	v_lshl_add_u64 v[146:147], s[50:51], 0, v[132:133]
	s_mov_b32 m0, s48
	s_nop 0
	global_load_lds_dwordx4 v[146:147], off
	v_lshl_add_u64 v[146:147], s[50:51], 0, v[136:137]
	s_add_i32 m0, s48, 0x2000
	s_nop 0
	global_load_lds_dwordx4 v[146:147], off
	v_lshl_add_u64 v[146:147], v[230:231], 0, s[26:27]
	s_mov_b32 m0, s43
	s_nop 0
	global_load_lds_dwordx4 v[146:147], off
	v_lshl_add_u64 v[146:147], v[232:233], 0, s[26:27]
	s_mov_b32 m0, s44
	s_nop 0
	global_load_lds_dwordx4 v[146:147], off
	s_waitcnt vmcnt(8)
	s_waitcnt lgkmcnt(0)
	s_barrier
	s_setprio 1
	s_waitcnt lgkmcnt(0)
	v_mfma_f32_16x16x32_bf16 v[60:63], v[166:169], v[198:201], v[60:63]
	v_mfma_f32_16x16x32_bf16 v[56:59], v[174:177], v[198:201], v[56:59]
	v_mfma_f32_16x16x32_bf16 v[44:47], v[166:169], v[206:209], v[44:47]
	v_mfma_f32_16x16x32_bf16 v[40:43], v[174:177], v[206:209], v[40:43]
	v_mfma_f32_16x16x32_bf16 v[28:31], v[166:169], v[214:217], v[28:31]
	v_mfma_f32_16x16x32_bf16 v[24:27], v[174:177], v[214:217], v[24:27]
	v_mfma_f32_16x16x32_bf16 v[12:15], v[166:169], v[222:225], v[12:15]
	v_mfma_f32_16x16x32_bf16 v[8:11], v[174:177], v[222:225], v[8:11]
	v_mfma_f32_16x16x32_bf16 v[60:63], v[170:173], v[202:205], v[60:63]
	v_mfma_f32_16x16x32_bf16 v[56:59], v[178:181], v[202:205], v[56:59]
	v_mfma_f32_16x16x32_bf16 v[44:47], v[170:173], v[210:213], v[44:47]
	v_mfma_f32_16x16x32_bf16 v[40:43], v[178:181], v[210:213], v[40:43]
	v_mfma_f32_16x16x32_bf16 v[28:31], v[170:173], v[218:221], v[28:31]
	v_mfma_f32_16x16x32_bf16 v[24:27], v[178:181], v[218:221], v[24:27]
	v_mfma_f32_16x16x32_bf16 v[12:15], v[170:173], v[226:229], v[12:15]
	v_mfma_f32_16x16x32_bf16 v[8:11], v[178:181], v[226:229], v[8:11]
	v_mfma_f32_16x16x32_bf16 v[52:55], v[182:185], v[198:201], v[52:55]
	v_mfma_f32_16x16x32_bf16 v[48:51], v[190:193], v[198:201], v[48:51]
	v_mfma_f32_16x16x32_bf16 v[36:39], v[182:185], v[206:209], v[36:39]
	v_mfma_f32_16x16x32_bf16 v[32:35], v[190:193], v[206:209], v[32:35]
	v_mfma_f32_16x16x32_bf16 v[20:23], v[182:185], v[214:217], v[20:23]
	v_mfma_f32_16x16x32_bf16 v[16:19], v[190:193], v[214:217], v[16:19]
	v_mfma_f32_16x16x32_bf16 v[4:7], v[182:185], v[222:225], v[4:7]
	v_mfma_f32_16x16x32_bf16 v[0:3], v[190:193], v[222:225], v[0:3]
	v_mfma_f32_16x16x32_bf16 v[52:55], v[186:189], v[202:205], v[52:55]
	v_mfma_f32_16x16x32_bf16 v[48:51], v[194:197], v[202:205], v[48:51]
	v_mfma_f32_16x16x32_bf16 v[36:39], v[186:189], v[210:213], v[36:39]
	v_mfma_f32_16x16x32_bf16 v[32:35], v[194:197], v[210:213], v[32:35]
	v_mfma_f32_16x16x32_bf16 v[20:23], v[186:189], v[218:221], v[20:23]
	v_mfma_f32_16x16x32_bf16 v[16:19], v[194:197], v[218:221], v[16:19]
	v_mfma_f32_16x16x32_bf16 v[4:7], v[186:189], v[226:229], v[4:7]
	v_mfma_f32_16x16x32_bf16 v[0:3], v[194:197], v[226:229], v[0:3]
	s_add_u32 s68, s68, 0x100
	s_addc_u32 s69, s69, 0
	s_add_u32 s34, s34, 0x100
	s_addc_u32 s42, s42, 0
	s_cmp_ge_u32 s49, s2
	s_mov_b32 s48, s49
	s_setprio 0
	s_barrier
	s_cbranch_scc0 .LBB0_1506
	s_xor_b64 s[66:67], s[66:67], -1
	s_and_b64 vcc, exec, s[36:37]
	s_cbranch_vccz .LBB0_1528

.LBB0_1658:
	ds_read_b128 v[152:155], v149
	ds_read_b128 v[156:159], v149 offset:1024
	ds_read_b128 v[160:163], v149 offset:2048
	ds_read_b128 v[166:169], v149 offset:3072
	ds_read_b128 v[170:173], v150
	ds_read_b128 v[174:177], v150 offset:1024
	ds_read_b128 v[178:181], v150 offset:2048
	ds_read_b128 v[182:185], v150 offset:3072
	s_add_u32 s50, s58, 0xfffc0080
	s_addc_u32 s51, s59, -1
	s_cmp_eq_u32 s49, 12
	s_cselect_b32 s63, s33, s51
	s_cselect_b32 s62, s34, s50
	s_cselect_b32 s61, s37, s48
	s_cselect_b32 s60, s39, s42
	v_lshl_add_u64 v[218:219], s[58:59], 0, v[140:141]
	s_add_i32 m0, s18, 0xc000
	ds_read_b128 v[186:189], v151
	ds_read_b128 v[190:193], v151 offset:1024
	ds_read_b128 v[194:197], v151 offset:2048
	ds_read_b128 v[198:201], v151 offset:3072
	ds_read_b128 v[202:205], v151 offset:4096
	ds_read_b128 v[206:209], v151 offset:5120
	ds_read_b128 v[210:213], v151 offset:6144
	ds_read_b128 v[214:217], v151 offset:7168
	global_load_lds_dwordx4 v[218:219], off
	v_lshl_add_u64 v[218:219], s[58:59], 0, v[142:143]
	s_add_i32 m0, s18, 0xe000
	s_nop 0
	global_load_lds_dwordx4 v[218:219], off
	s_waitcnt vmcnt(8)
	s_waitcnt lgkmcnt(0)
	s_barrier
	s_setprio 1
	s_waitcnt lgkmcnt(0)
	v_mfma_f32_16x16x32_bf16 v[124:127], v[152:155], v[186:189], v[124:127]
	v_mfma_f32_16x16x32_bf16 v[120:123], v[160:163], v[186:189], v[120:123]
	v_mfma_f32_16x16x32_bf16 v[108:111], v[152:155], v[194:197], v[108:111]
	v_mfma_f32_16x16x32_bf16 v[104:107], v[160:163], v[194:197], v[104:107]
	v_mfma_f32_16x16x32_bf16 v[92:95], v[152:155], v[202:205], v[92:95]
	v_mfma_f32_16x16x32_bf16 v[88:91], v[160:163], v[202:205], v[88:91]
	v_mfma_f32_16x16x32_bf16 v[76:79], v[152:155], v[210:213], v[76:79]
	v_mfma_f32_16x16x32_bf16 v[72:75], v[160:163], v[210:213], v[72:75]
	v_mfma_f32_16x16x32_bf16 v[124:127], v[156:159], v[190:193], v[124:127]
	v_mfma_f32_16x16x32_bf16 v[120:123], v[166:169], v[190:193], v[120:123]
	v_mfma_f32_16x16x32_bf16 v[108:111], v[156:159], v[198:201], v[108:111]
	v_mfma_f32_16x16x32_bf16 v[104:107], v[166:169], v[198:201], v[104:107]
	v_mfma_f32_16x16x32_bf16 v[92:95], v[156:159], v[206:209], v[92:95]
	v_mfma_f32_16x16x32_bf16 v[88:91], v[166:169], v[206:209], v[88:91]
	v_mfma_f32_16x16x32_bf16 v[76:79], v[156:159], v[214:217], v[76:79]
	v_mfma_f32_16x16x32_bf16 v[72:75], v[166:169], v[214:217], v[72:75]
	v_mfma_f32_16x16x32_bf16 v[116:119], v[170:173], v[186:189], v[116:119]
	v_mfma_f32_16x16x32_bf16 v[112:115], v[178:181], v[186:189], v[112:115]
	v_mfma_f32_16x16x32_bf16 v[100:103], v[170:173], v[194:197], v[100:103]
	v_mfma_f32_16x16x32_bf16 v[96:99], v[178:181], v[194:197], v[96:99]
	v_mfma_f32_16x16x32_bf16 v[84:87], v[170:173], v[202:205], v[84:87]
	v_mfma_f32_16x16x32_bf16 v[80:83], v[178:181], v[202:205], v[80:83]
	v_mfma_f32_16x16x32_bf16 v[68:71], v[170:173], v[210:213], v[68:71]
	v_mfma_f32_16x16x32_bf16 v[64:67], v[178:181], v[210:213], v[64:67]
	v_mfma_f32_16x16x32_bf16 v[116:119], v[174:177], v[190:193], v[116:119]
	v_mfma_f32_16x16x32_bf16 v[112:115], v[182:185], v[190:193], v[112:115]
	v_mfma_f32_16x16x32_bf16 v[100:103], v[174:177], v[198:201], v[100:103]
	v_mfma_f32_16x16x32_bf16 v[96:99], v[182:185], v[198:201], v[96:99]
	v_mfma_f32_16x16x32_bf16 v[84:87], v[174:177], v[206:209], v[84:87]
	v_mfma_f32_16x16x32_bf16 v[80:83], v[182:185], v[206:209], v[80:83]
	v_mfma_f32_16x16x32_bf16 v[68:71], v[174:177], v[214:217], v[68:71]
	v_mfma_f32_16x16x32_bf16 v[64:67], v[182:185], v[214:217], v[64:67]
	s_setprio 0
	s_barrier
	s_add_i32 s50, s64, s3
	v_lshl_add_u64 v[218:219], s[60:61], 0, v[134:135]
	s_mov_b32 m0, s50
	ds_read_b128 v[186:189], v151 offset:16384
	ds_read_b128 v[190:193], v151 offset:17408
	ds_read_b128 v[194:197], v151 offset:18432
	ds_read_b128 v[198:201], v151 offset:19456
	ds_read_b128 v[202:205], v151 offset:20480
	ds_read_b128 v[206:209], v151 offset:21504
	ds_read_b128 v[210:213], v151 offset:22528
	ds_read_b128 v[214:217], v151 offset:23552
	global_load_lds_dwordx4 v[218:219], off
	s_add_i32 m0, s50, 0x2000
	s_add_u32 s50, s60, 0x40000
	v_lshl_add_u64 v[220:221], s[60:61], 0, v[130:131]
	s_addc_u32 s51, s61, 0
	s_add_i32 s57, s65, s3
	global_load_lds_dwordx4 v[220:221], off
	v_lshl_add_u64 v[222:223], s[50:51], 0, v[134:135]
	s_mov_b32 m0, s57
	v_lshl_add_u64 v[224:225], s[62:63], 0, v[132:133]
	global_load_lds_dwordx4 v[222:223], off
	v_lshl_add_u64 v[222:223], s[50:51], 0, v[130:131]
	s_add_i32 m0, s57, 0x2000
	s_nop 0
	global_load_lds_dwordx4 v[222:223], off
	v_lshl_add_u64 v[222:223], s[62:63], 0, v[136:137]
	s_mov_b32 m0, s18
	s_nop 0
	global_load_lds_dwordx4 v[222:223], off
	s_mov_b32 m0, s19
	s_nop 0
	global_load_lds_dwordx4 v[224:225], off
	s_waitcnt vmcnt(8)
	s_waitcnt lgkmcnt(0)
	s_barrier
	s_setprio 1
	s_waitcnt lgkmcnt(0)
	v_mfma_f32_16x16x32_bf16 v[60:63], v[152:155], v[186:189], v[60:63]
	v_mfma_f32_16x16x32_bf16 v[56:59], v[160:163], v[186:189], v[56:59]
	v_mfma_f32_16x16x32_bf16 v[44:47], v[152:155], v[194:197], v[44:47]
	v_mfma_f32_16x16x32_bf16 v[40:43], v[160:163], v[194:197], v[40:43]
	v_mfma_f32_16x16x32_bf16 v[28:31], v[152:155], v[202:205], v[28:31]
	v_mfma_f32_16x16x32_bf16 v[24:27], v[160:163], v[202:205], v[24:27]
	v_mfma_f32_16x16x32_bf16 v[12:15], v[152:155], v[210:213], v[12:15]
	v_mfma_f32_16x16x32_bf16 v[8:11], v[160:163], v[210:213], v[8:11]
	v_mfma_f32_16x16x32_bf16 v[60:63], v[156:159], v[190:193], v[60:63]
	v_mfma_f32_16x16x32_bf16 v[56:59], v[166:169], v[190:193], v[56:59]
	v_mfma_f32_16x16x32_bf16 v[44:47], v[156:159], v[198:201], v[44:47]
	v_mfma_f32_16x16x32_bf16 v[40:43], v[166:169], v[198:201], v[40:43]
	v_mfma_f32_16x16x32_bf16 v[28:31], v[156:159], v[206:209], v[28:31]
	v_mfma_f32_16x16x32_bf16 v[24:27], v[166:169], v[206:209], v[24:27]
	v_mfma_f32_16x16x32_bf16 v[12:15], v[156:159], v[214:217], v[12:15]
	v_mfma_f32_16x16x32_bf16 v[8:11], v[166:169], v[214:217], v[8:11]
	v_mfma_f32_16x16x32_bf16 v[52:55], v[170:173], v[186:189], v[52:55]
	v_mfma_f32_16x16x32_bf16 v[48:51], v[178:181], v[186:189], v[48:51]
	v_mfma_f32_16x16x32_bf16 v[36:39], v[170:173], v[194:197], v[36:39]
	v_mfma_f32_16x16x32_bf16 v[32:35], v[178:181], v[194:197], v[32:35]
	v_mfma_f32_16x16x32_bf16 v[20:23], v[170:173], v[202:205], v[20:23]
	v_mfma_f32_16x16x32_bf16 v[16:19], v[178:181], v[202:205], v[16:19]
	v_mfma_f32_16x16x32_bf16 v[4:7], v[170:173], v[210:213], v[4:7]
	v_mfma_f32_16x16x32_bf16 v[0:3], v[178:181], v[210:213], v[0:3]
	v_mfma_f32_16x16x32_bf16 v[52:55], v[174:177], v[190:193], v[52:55]
	v_mfma_f32_16x16x32_bf16 v[48:51], v[182:185], v[190:193], v[48:51]
	v_mfma_f32_16x16x32_bf16 v[36:39], v[174:177], v[198:201], v[36:39]
	v_mfma_f32_16x16x32_bf16 v[32:35], v[182:185], v[198:201], v[32:35]
	v_mfma_f32_16x16x32_bf16 v[20:23], v[174:177], v[206:209], v[20:23]
	v_mfma_f32_16x16x32_bf16 v[16:19], v[182:185], v[206:209], v[16:19]
	v_mfma_f32_16x16x32_bf16 v[4:7], v[174:177], v[214:217], v[4:7]
	v_mfma_f32_16x16x32_bf16 v[0:3], v[182:185], v[214:217], v[0:3]
	s_setprio 0
	s_barrier
	s_add_i32 s57, 0, 0x18000
	v_add_u32_e32 v165, s57, v148
	s_add_i32 s68, 0, 0x1c000
	ds_read_b128 v[152:155], v165
	ds_read_b128 v[156:159], v165 offset:1024
	ds_read_b128 v[160:163], v165 offset:2048
	ds_read_b128 v[166:169], v165 offset:3072
	v_add_u32_e32 v165, s68, v148
	ds_read_b128 v[170:173], v165
	ds_read_b128 v[174:177], v165 offset:1024
	ds_read_b128 v[178:181], v165 offset:2048
	ds_read_b128 v[182:185], v165 offset:3072
	s_add_u32 s50, s62, 0x40000
	s_addc_u32 s51, s63, 0
	s_mov_b32 m0, s35
	v_lshl_add_u64 v[226:227], s[50:51], 0, v[136:137]
	ds_read_b128 v[186:189], v151 offset:32768
	ds_read_b128 v[190:193], v151 offset:33792
	ds_read_b128 v[194:197], v151 offset:34816
	ds_read_b128 v[198:201], v151 offset:35840
	ds_read_b128 v[202:205], v151 offset:36864
	ds_read_b128 v[206:209], v151 offset:37888
	ds_read_b128 v[210:213], v151 offset:38912
	ds_read_b128 v[214:217], v151 offset:39936
	global_load_lds_dwordx4 v[226:227], off
	v_lshl_add_u64 v[226:227], s[50:51], 0, v[132:133]
	s_mov_b32 m0, s43
	s_nop 0
	global_load_lds_dwordx4 v[226:227], off
	s_waitcnt vmcnt(8)
	s_waitcnt lgkmcnt(0)
	s_barrier
	s_setprio 1
	s_waitcnt lgkmcnt(0)
	v_mfma_f32_16x16x32_bf16 v[124:127], v[152:155], v[186:189], v[124:127]
	v_mfma_f32_16x16x32_bf16 v[120:123], v[160:163], v[186:189], v[120:123]
	v_mfma_f32_16x16x32_bf16 v[108:111], v[152:155], v[194:197], v[108:111]
	v_mfma_f32_16x16x32_bf16 v[104:107], v[160:163], v[194:197], v[104:107]
	v_mfma_f32_16x16x32_bf16 v[92:95], v[152:155], v[202:205], v[92:95]
	v_mfma_f32_16x16x32_bf16 v[88:91], v[160:163], v[202:205], v[88:91]
	v_mfma_f32_16x16x32_bf16 v[76:79], v[152:155], v[210:213], v[76:79]
	v_mfma_f32_16x16x32_bf16 v[72:75], v[160:163], v[210:213], v[72:75]
	v_mfma_f32_16x16x32_bf16 v[124:127], v[156:159], v[190:193], v[124:127]
	v_mfma_f32_16x16x32_bf16 v[120:123], v[166:169], v[190:193], v[120:123]
	v_mfma_f32_16x16x32_bf16 v[108:111], v[156:159], v[198:201], v[108:111]
	v_mfma_f32_16x16x32_bf16 v[104:107], v[166:169], v[198:201], v[104:107]
	v_mfma_f32_16x16x32_bf16 v[92:95], v[156:159], v[206:209], v[92:95]
	v_mfma_f32_16x16x32_bf16 v[88:91], v[166:169], v[206:209], v[88:91]
	v_mfma_f32_16x16x32_bf16 v[76:79], v[156:159], v[214:217], v[76:79]
	v_mfma_f32_16x16x32_bf16 v[72:75], v[166:169], v[214:217], v[72:75]
	v_mfma_f32_16x16x32_bf16 v[116:119], v[170:173], v[186:189], v[116:119]
	v_mfma_f32_16x16x32_bf16 v[112:115], v[178:181], v[186:189], v[112:115]
	v_mfma_f32_16x16x32_bf16 v[100:103], v[170:173], v[194:197], v[100:103]
	v_mfma_f32_16x16x32_bf16 v[96:99], v[178:181], v[194:197], v[96:99]
	v_mfma_f32_16x16x32_bf16 v[84:87], v[170:173], v[202:205], v[84:87]
	v_mfma_f32_16x16x32_bf16 v[80:83], v[178:181], v[202:205], v[80:83]
	v_mfma_f32_16x16x32_bf16 v[68:71], v[170:173], v[210:213], v[68:71]
	v_mfma_f32_16x16x32_bf16 v[64:67], v[178:181], v[210:213], v[64:67]
	v_mfma_f32_16x16x32_bf16 v[116:119], v[174:177], v[190:193], v[116:119]
	v_mfma_f32_16x16x32_bf16 v[112:115], v[182:185], v[190:193], v[112:115]
	v_mfma_f32_16x16x32_bf16 v[100:103], v[174:177], v[198:201], v[100:103]
	v_mfma_f32_16x16x32_bf16 v[96:99], v[182:185], v[198:201], v[96:99]
	v_mfma_f32_16x16x32_bf16 v[84:87], v[174:177], v[206:209], v[84:87]
	v_mfma_f32_16x16x32_bf16 v[80:83], v[182:185], v[206:209], v[80:83]
	v_mfma_f32_16x16x32_bf16 v[68:71], v[174:177], v[214:217], v[68:71]
	v_mfma_f32_16x16x32_bf16 v[64:67], v[182:185], v[214:217], v[64:67]
	s_setprio 0
	s_barrier
	s_add_i32 s50, s57, s3
	v_lshl_add_u64 v[218:219], v[218:219], 0, s[24:25]
	s_mov_b32 m0, s50
	ds_read_b128 v[186:189], v151 offset:49152
	ds_read_b128 v[190:193], v151 offset:50176
	ds_read_b128 v[194:197], v151 offset:51200
	ds_read_b128 v[198:201], v151 offset:52224
	ds_read_b128 v[202:205], v151 offset:53248
	ds_read_b128 v[206:209], v151 offset:54272
	ds_read_b128 v[210:213], v151 offset:55296
	ds_read_b128 v[214:217], v151 offset:56320
	global_load_lds_dwordx4 v[218:219], off
	s_add_i32 m0, s50, 0x2000
	s_add_u32 s50, s60, 0x40080
	v_lshl_add_u64 v[218:219], v[220:221], 0, s[24:25]
	s_addc_u32 s51, s61, 0
	s_add_i32 s57, s68, s3
	global_load_lds_dwordx4 v[218:219], off
	v_lshl_add_u64 v[218:219], s[50:51], 0, v[134:135]
	s_mov_b32 m0, s57
	s_nop 0
	global_load_lds_dwordx4 v[218:219], off
	v_lshl_add_u64 v[218:219], s[50:51], 0, v[130:131]
	s_add_i32 m0, s57, 0x2000
	s_nop 0
	global_load_lds_dwordx4 v[218:219], off
	v_lshl_add_u64 v[218:219], v[222:223], 0, s[24:25]
	s_mov_b32 m0, s44
	s_nop 0
	global_load_lds_dwordx4 v[218:219], off
	v_lshl_add_u64 v[218:219], v[224:225], 0, s[24:25]
	s_mov_b32 m0, s45
	s_nop 0
	global_load_lds_dwordx4 v[218:219], off
	s_waitcnt vmcnt(8)
	s_waitcnt lgkmcnt(0)
	s_barrier
	s_setprio 1
	s_waitcnt lgkmcnt(0)
	v_mfma_f32_16x16x32_bf16 v[60:63], v[152:155], v[186:189], v[60:63]
	v_mfma_f32_16x16x32_bf16 v[56:59], v[160:163], v[186:189], v[56:59]
	v_mfma_f32_16x16x32_bf16 v[44:47], v[152:155], v[194:197], v[44:47]
	v_mfma_f32_16x16x32_bf16 v[40:43], v[160:163], v[194:197], v[40:43]
	v_mfma_f32_16x16x32_bf16 v[28:31], v[152:155], v[202:205], v[28:31]
	v_mfma_f32_16x16x32_bf16 v[24:27], v[160:163], v[202:205], v[24:27]
	v_mfma_f32_16x16x32_bf16 v[12:15], v[152:155], v[210:213], v[12:15]
	v_mfma_f32_16x16x32_bf16 v[8:11], v[160:163], v[210:213], v[8:11]
	v_mfma_f32_16x16x32_bf16 v[60:63], v[156:159], v[190:193], v[60:63]
	v_mfma_f32_16x16x32_bf16 v[56:59], v[166:169], v[190:193], v[56:59]
	v_mfma_f32_16x16x32_bf16 v[44:47], v[156:159], v[198:201], v[44:47]
	v_mfma_f32_16x16x32_bf16 v[40:43], v[166:169], v[198:201], v[40:43]
	v_mfma_f32_16x16x32_bf16 v[28:31], v[156:159], v[206:209], v[28:31]
	v_mfma_f32_16x16x32_bf16 v[24:27], v[166:169], v[206:209], v[24:27]
	v_mfma_f32_16x16x32_bf16 v[12:15], v[156:159], v[214:217], v[12:15]
	v_mfma_f32_16x16x32_bf16 v[8:11], v[166:169], v[214:217], v[8:11]
	v_mfma_f32_16x16x32_bf16 v[52:55], v[170:173], v[186:189], v[52:55]
	v_mfma_f32_16x16x32_bf16 v[48:51], v[178:181], v[186:189], v[48:51]
	v_mfma_f32_16x16x32_bf16 v[36:39], v[170:173], v[194:197], v[36:39]
	v_mfma_f32_16x16x32_bf16 v[32:35], v[178:181], v[194:197], v[32:35]
	v_mfma_f32_16x16x32_bf16 v[20:23], v[170:173], v[202:205], v[20:23]
	v_mfma_f32_16x16x32_bf16 v[16:19], v[178:181], v[202:205], v[16:19]
	v_mfma_f32_16x16x32_bf16 v[4:7], v[170:173], v[210:213], v[4:7]
	v_mfma_f32_16x16x32_bf16 v[0:3], v[178:181], v[210:213], v[0:3]
	v_mfma_f32_16x16x32_bf16 v[52:55], v[174:177], v[190:193], v[52:55]
	v_mfma_f32_16x16x32_bf16 v[48:51], v[182:185], v[190:193], v[48:51]
	v_mfma_f32_16x16x32_bf16 v[36:39], v[174:177], v[198:201], v[36:39]
	v_mfma_f32_16x16x32_bf16 v[32:35], v[182:185], v[198:201], v[32:35]
	v_mfma_f32_16x16x32_bf16 v[20:23], v[174:177], v[206:209], v[20:23]
	v_mfma_f32_16x16x32_bf16 v[16:19], v[182:185], v[206:209], v[16:19]
	v_mfma_f32_16x16x32_bf16 v[4:7], v[174:177], v[214:217], v[4:7]
	v_mfma_f32_16x16x32_bf16 v[0:3], v[182:185], v[214:217], v[0:3]
	s_add_i32 s49, s49, 2
	s_add_u32 s58, s58, 0x100
	s_addc_u32 s59, s59, 0
	s_add_u32 s42, s42, 0x100
	s_addc_u32 s48, s48, 0
	s_cmp_gt_u32 s49, 13
	s_setprio 0
	s_barrier
	s_cbranch_scc0 .LBB0_1658
	s_and_b64 vcc, exec, s[26:27]
	s_cbranch_vccz .LBB0_1661
	s_barrier

.LBB0_1735:
	ds_read_b128 v[162:165], v159
	ds_read_b128 v[166:169], v159 offset:1024
	ds_read_b128 v[170:173], v159 offset:2048
	ds_read_b128 v[174:177], v159 offset:3072
	ds_read_b128 v[178:181], v160
	ds_read_b128 v[182:185], v160 offset:1024
	ds_read_b128 v[186:189], v160 offset:2048
	ds_read_b128 v[190:193], v160 offset:3072
	s_add_i32 s68, s56, 2
	s_add_u32 s54, s52, 0x100
	s_addc_u32 s55, s53, 0
	s_cmp_eq_u32 s34, s56
	s_cselect_b32 s56, s48, s37
	s_cselect_b32 s59, s39, s55
	s_cselect_b32 s58, s38, s54
	s_cselect_b32 s57, s49, s42
	v_lshl_add_u64 v[146:147], s[52:53], 0, v[142:143]
	s_add_i32 m0, s18, 0xc000
	ds_read_b128 v[194:197], v161
	ds_read_b128 v[198:201], v161 offset:1024
	ds_read_b128 v[202:205], v161 offset:2048
	ds_read_b128 v[206:209], v161 offset:3072
	ds_read_b128 v[210:213], v161 offset:4096
	ds_read_b128 v[214:217], v161 offset:5120
	ds_read_b128 v[218:221], v161 offset:6144
	ds_read_b128 v[222:225], v161 offset:7168
	global_load_lds_dwordx4 v[146:147], off
	v_lshl_add_u64 v[146:147], s[52:53], 0, v[144:145]
	s_add_i32 m0, s18, 0xe000
	s_nop 0
	global_load_lds_dwordx4 v[146:147], off
	s_waitcnt vmcnt(8)
	s_waitcnt lgkmcnt(0)
	s_barrier
	s_setprio 1
	s_waitcnt lgkmcnt(0)
	v_mfma_f32_16x16x32_bf16 v[124:127], v[162:165], v[194:197], v[124:127]
	v_mfma_f32_16x16x32_bf16 v[120:123], v[170:173], v[194:197], v[120:123]
	v_mfma_f32_16x16x32_bf16 v[108:111], v[162:165], v[202:205], v[108:111]
	v_mfma_f32_16x16x32_bf16 v[104:107], v[170:173], v[202:205], v[104:107]
	v_mfma_f32_16x16x32_bf16 v[92:95], v[162:165], v[210:213], v[92:95]
	v_mfma_f32_16x16x32_bf16 v[88:91], v[170:173], v[210:213], v[88:91]
	v_mfma_f32_16x16x32_bf16 v[76:79], v[162:165], v[218:221], v[76:79]
	v_mfma_f32_16x16x32_bf16 v[72:75], v[170:173], v[218:221], v[72:75]
	v_mfma_f32_16x16x32_bf16 v[124:127], v[166:169], v[198:201], v[124:127]
	v_mfma_f32_16x16x32_bf16 v[120:123], v[174:177], v[198:201], v[120:123]
	v_mfma_f32_16x16x32_bf16 v[108:111], v[166:169], v[206:209], v[108:111]
	v_mfma_f32_16x16x32_bf16 v[104:107], v[174:177], v[206:209], v[104:107]
	v_mfma_f32_16x16x32_bf16 v[92:95], v[166:169], v[214:217], v[92:95]
	v_mfma_f32_16x16x32_bf16 v[88:91], v[174:177], v[214:217], v[88:91]
	v_mfma_f32_16x16x32_bf16 v[76:79], v[166:169], v[222:225], v[76:79]
	v_mfma_f32_16x16x32_bf16 v[72:75], v[174:177], v[222:225], v[72:75]
	v_mfma_f32_16x16x32_bf16 v[116:119], v[178:181], v[194:197], v[116:119]
	v_mfma_f32_16x16x32_bf16 v[112:115], v[186:189], v[194:197], v[112:115]
	v_mfma_f32_16x16x32_bf16 v[100:103], v[178:181], v[202:205], v[100:103]
	v_mfma_f32_16x16x32_bf16 v[96:99], v[186:189], v[202:205], v[96:99]
	v_mfma_f32_16x16x32_bf16 v[84:87], v[178:181], v[210:213], v[84:87]
	v_mfma_f32_16x16x32_bf16 v[80:83], v[186:189], v[210:213], v[80:83]
	v_mfma_f32_16x16x32_bf16 v[68:71], v[178:181], v[218:221], v[68:71]
	v_mfma_f32_16x16x32_bf16 v[64:67], v[186:189], v[218:221], v[64:67]
	v_mfma_f32_16x16x32_bf16 v[116:119], v[182:185], v[198:201], v[116:119]
	v_mfma_f32_16x16x32_bf16 v[112:115], v[190:193], v[198:201], v[112:115]
	v_mfma_f32_16x16x32_bf16 v[100:103], v[182:185], v[206:209], v[100:103]
	v_mfma_f32_16x16x32_bf16 v[96:99], v[190:193], v[206:209], v[96:99]
	v_mfma_f32_16x16x32_bf16 v[84:87], v[182:185], v[214:217], v[84:87]
	v_mfma_f32_16x16x32_bf16 v[80:83], v[190:193], v[214:217], v[80:83]
	v_mfma_f32_16x16x32_bf16 v[68:71], v[182:185], v[222:225], v[68:71]
	v_mfma_f32_16x16x32_bf16 v[64:67], v[190:193], v[222:225], v[64:67]
	s_setprio 0
	s_barrier
	s_add_i32 s52, s63, s15
	v_lshl_add_u64 v[146:147], s[56:57], 0, v[132:133]
	s_mov_b32 m0, s52
	ds_read_b128 v[194:197], v161 offset:16384
	ds_read_b128 v[198:201], v161 offset:17408
	ds_read_b128 v[202:205], v161 offset:18432
	ds_read_b128 v[206:209], v161 offset:19456
	ds_read_b128 v[210:213], v161 offset:20480
	ds_read_b128 v[214:217], v161 offset:21504
	ds_read_b128 v[218:221], v161 offset:22528
	ds_read_b128 v[222:225], v161 offset:23552
	global_load_lds_dwordx4 v[146:147], off
	s_add_i32 m0, s52, 0x2000
	s_add_u32 s52, s56, 0xb0000
	v_lshl_add_u64 v[226:227], s[56:57], 0, v[136:137]
	s_addc_u32 s53, s57, 0
	s_add_i32 s69, s64, s15
	global_load_lds_dwordx4 v[226:227], off
	v_lshl_add_u64 v[228:229], s[52:53], 0, v[132:133]
	s_mov_b32 m0, s69
	v_lshl_add_u64 v[230:231], s[58:59], 0, v[134:135]
	global_load_lds_dwordx4 v[228:229], off
	v_lshl_add_u64 v[228:229], s[52:53], 0, v[136:137]
	s_add_i32 m0, s69, 0x2000
	s_nop 0
	global_load_lds_dwordx4 v[228:229], off
	v_lshl_add_u64 v[228:229], s[58:59], 0, v[130:131]
	s_mov_b32 m0, s18
	s_nop 0
	global_load_lds_dwordx4 v[228:229], off
	s_mov_b32 m0, s19
	s_nop 0
	global_load_lds_dwordx4 v[230:231], off
	s_waitcnt vmcnt(8)
	s_waitcnt lgkmcnt(0)
	s_barrier
	s_setprio 1
	s_waitcnt lgkmcnt(0)
	v_mfma_f32_16x16x32_bf16 v[60:63], v[162:165], v[194:197], v[60:63]
	v_mfma_f32_16x16x32_bf16 v[56:59], v[170:173], v[194:197], v[56:59]
	v_mfma_f32_16x16x32_bf16 v[44:47], v[162:165], v[202:205], v[44:47]
	v_mfma_f32_16x16x32_bf16 v[40:43], v[170:173], v[202:205], v[40:43]
	v_mfma_f32_16x16x32_bf16 v[28:31], v[162:165], v[210:213], v[28:31]
	v_mfma_f32_16x16x32_bf16 v[24:27], v[170:173], v[210:213], v[24:27]
	v_mfma_f32_16x16x32_bf16 v[12:15], v[162:165], v[218:221], v[12:15]
	v_mfma_f32_16x16x32_bf16 v[8:11], v[170:173], v[218:221], v[8:11]
	v_mfma_f32_16x16x32_bf16 v[60:63], v[166:169], v[198:201], v[60:63]
	v_mfma_f32_16x16x32_bf16 v[56:59], v[174:177], v[198:201], v[56:59]
	v_mfma_f32_16x16x32_bf16 v[44:47], v[166:169], v[206:209], v[44:47]
	v_mfma_f32_16x16x32_bf16 v[40:43], v[174:177], v[206:209], v[40:43]
	v_mfma_f32_16x16x32_bf16 v[28:31], v[166:169], v[214:217], v[28:31]
	v_mfma_f32_16x16x32_bf16 v[24:27], v[174:177], v[214:217], v[24:27]
	v_mfma_f32_16x16x32_bf16 v[12:15], v[166:169], v[222:225], v[12:15]
	v_mfma_f32_16x16x32_bf16 v[8:11], v[174:177], v[222:225], v[8:11]
	v_mfma_f32_16x16x32_bf16 v[52:55], v[178:181], v[194:197], v[52:55]
	v_mfma_f32_16x16x32_bf16 v[48:51], v[186:189], v[194:197], v[48:51]
	v_mfma_f32_16x16x32_bf16 v[36:39], v[178:181], v[202:205], v[36:39]
	v_mfma_f32_16x16x32_bf16 v[32:35], v[186:189], v[202:205], v[32:35]
	v_mfma_f32_16x16x32_bf16 v[20:23], v[178:181], v[210:213], v[20:23]
	v_mfma_f32_16x16x32_bf16 v[16:19], v[186:189], v[210:213], v[16:19]
	v_mfma_f32_16x16x32_bf16 v[4:7], v[178:181], v[218:221], v[4:7]
	v_mfma_f32_16x16x32_bf16 v[0:3], v[186:189], v[218:221], v[0:3]
	v_mfma_f32_16x16x32_bf16 v[52:55], v[182:185], v[198:201], v[52:55]
	v_mfma_f32_16x16x32_bf16 v[48:51], v[190:193], v[198:201], v[48:51]
	v_mfma_f32_16x16x32_bf16 v[36:39], v[182:185], v[206:209], v[36:39]
	v_mfma_f32_16x16x32_bf16 v[32:35], v[190:193], v[206:209], v[32:35]
	v_mfma_f32_16x16x32_bf16 v[20:23], v[182:185], v[214:217], v[20:23]
	v_mfma_f32_16x16x32_bf16 v[16:19], v[190:193], v[214:217], v[16:19]
	v_mfma_f32_16x16x32_bf16 v[4:7], v[182:185], v[222:225], v[4:7]
	v_mfma_f32_16x16x32_bf16 v[0:3], v[190:193], v[222:225], v[0:3]
	s_setprio 0
	s_barrier
	s_add_i32 s69, 0, 0x18000
	v_add_u32_e32 v138, s69, v141
	s_add_i32 s70, 0, 0x1c000
	ds_read_b128 v[162:165], v138
	ds_read_b128 v[166:169], v138 offset:1024
	ds_read_b128 v[170:173], v138 offset:2048
	ds_read_b128 v[174:177], v138 offset:3072
	v_add_u32_e32 v138, s70, v141
	ds_read_b128 v[178:181], v138
	ds_read_b128 v[182:185], v138 offset:1024
	ds_read_b128 v[186:189], v138 offset:2048
	ds_read_b128 v[190:193], v138 offset:3072
	s_add_u32 s52, s58, 0xb0000
	s_addc_u32 s53, s59, 0
	s_mov_b32 m0, s35
	v_lshl_add_u64 v[232:233], s[52:53], 0, v[130:131]
	ds_read_b128 v[194:197], v161 offset:32768
	ds_read_b128 v[198:201], v161 offset:33792
	ds_read_b128 v[202:205], v161 offset:34816
	ds_read_b128 v[206:209], v161 offset:35840
	ds_read_b128 v[210:213], v161 offset:36864
	ds_read_b128 v[214:217], v161 offset:37888
	ds_read_b128 v[218:221], v161 offset:38912
	ds_read_b128 v[222:225], v161 offset:39936
	global_load_lds_dwordx4 v[232:233], off
	v_lshl_add_u64 v[232:233], s[52:53], 0, v[134:135]
	s_mov_b32 m0, s43
	s_nop 0
	global_load_lds_dwordx4 v[232:233], off
	s_waitcnt vmcnt(8)
	s_waitcnt lgkmcnt(0)
	s_barrier
	s_setprio 1
	s_waitcnt lgkmcnt(0)
	v_mfma_f32_16x16x32_bf16 v[124:127], v[162:165], v[194:197], v[124:127]
	v_mfma_f32_16x16x32_bf16 v[120:123], v[170:173], v[194:197], v[120:123]
	v_mfma_f32_16x16x32_bf16 v[108:111], v[162:165], v[202:205], v[108:111]
	v_mfma_f32_16x16x32_bf16 v[104:107], v[170:173], v[202:205], v[104:107]
	v_mfma_f32_16x16x32_bf16 v[92:95], v[162:165], v[210:213], v[92:95]
	v_mfma_f32_16x16x32_bf16 v[88:91], v[170:173], v[210:213], v[88:91]
	v_mfma_f32_16x16x32_bf16 v[76:79], v[162:165], v[218:221], v[76:79]
	v_mfma_f32_16x16x32_bf16 v[72:75], v[170:173], v[218:221], v[72:75]
	v_mfma_f32_16x16x32_bf16 v[124:127], v[166:169], v[198:201], v[124:127]
	v_mfma_f32_16x16x32_bf16 v[120:123], v[174:177], v[198:201], v[120:123]
	v_mfma_f32_16x16x32_bf16 v[108:111], v[166:169], v[206:209], v[108:111]
	v_mfma_f32_16x16x32_bf16 v[104:107], v[174:177], v[206:209], v[104:107]
	v_mfma_f32_16x16x32_bf16 v[92:95], v[166:169], v[214:217], v[92:95]
	v_mfma_f32_16x16x32_bf16 v[88:91], v[174:177], v[214:217], v[88:91]
	v_mfma_f32_16x16x32_bf16 v[76:79], v[166:169], v[222:225], v[76:79]
	v_mfma_f32_16x16x32_bf16 v[72:75], v[174:177], v[222:225], v[72:75]
	v_mfma_f32_16x16x32_bf16 v[116:119], v[178:181], v[194:197], v[116:119]
	v_mfma_f32_16x16x32_bf16 v[112:115], v[186:189], v[194:197], v[112:115]
	v_mfma_f32_16x16x32_bf16 v[100:103], v[178:181], v[202:205], v[100:103]
	v_mfma_f32_16x16x32_bf16 v[96:99], v[186:189], v[202:205], v[96:99]
	v_mfma_f32_16x16x32_bf16 v[84:87], v[178:181], v[210:213], v[84:87]
	v_mfma_f32_16x16x32_bf16 v[80:83], v[186:189], v[210:213], v[80:83]
	v_mfma_f32_16x16x32_bf16 v[68:71], v[178:181], v[218:221], v[68:71]
	v_mfma_f32_16x16x32_bf16 v[64:67], v[186:189], v[218:221], v[64:67]
	v_mfma_f32_16x16x32_bf16 v[116:119], v[182:185], v[198:201], v[116:119]
	v_mfma_f32_16x16x32_bf16 v[112:115], v[190:193], v[198:201], v[112:115]
	v_mfma_f32_16x16x32_bf16 v[100:103], v[182:185], v[206:209], v[100:103]
	v_mfma_f32_16x16x32_bf16 v[96:99], v[190:193], v[206:209], v[96:99]
	v_mfma_f32_16x16x32_bf16 v[84:87], v[182:185], v[214:217], v[84:87]
	v_mfma_f32_16x16x32_bf16 v[80:83], v[190:193], v[214:217], v[80:83]
	v_mfma_f32_16x16x32_bf16 v[68:71], v[182:185], v[222:225], v[68:71]
	v_mfma_f32_16x16x32_bf16 v[64:67], v[190:193], v[222:225], v[64:67]
	s_setprio 0
	s_barrier
	s_add_i32 s52, s69, s15
	v_lshl_add_u64 v[146:147], v[146:147], 0, s[22:23]
	s_mov_b32 m0, s52
	ds_read_b128 v[194:197], v161 offset:49152
	ds_read_b128 v[198:201], v161 offset:50176
	ds_read_b128 v[202:205], v161 offset:51200
	ds_read_b128 v[206:209], v161 offset:52224
	ds_read_b128 v[210:213], v161 offset:53248
	ds_read_b128 v[214:217], v161 offset:54272
	ds_read_b128 v[218:221], v161 offset:55296
	ds_read_b128 v[222:225], v161 offset:56320
	global_load_lds_dwordx4 v[146:147], off
	s_add_i32 m0, s52, 0x2000
	s_add_u32 s52, s56, 0xb0080
	v_lshl_add_u64 v[146:147], v[226:227], 0, s[22:23]
	s_addc_u32 s53, s57, 0
	s_add_i32 s56, s70, s15
	global_load_lds_dwordx4 v[146:147], off
	v_lshl_add_u64 v[146:147], s[52:53], 0, v[132:133]
	s_mov_b32 m0, s56
	s_nop 0
	global_load_lds_dwordx4 v[146:147], off
	v_lshl_add_u64 v[146:147], s[52:53], 0, v[136:137]
	s_add_i32 m0, s56, 0x2000
	s_nop 0
	global_load_lds_dwordx4 v[146:147], off
	v_lshl_add_u64 v[146:147], v[228:229], 0, s[22:23]
	s_mov_b32 m0, s46
	s_nop 0
	global_load_lds_dwordx4 v[146:147], off
	v_lshl_add_u64 v[146:147], v[230:231], 0, s[22:23]
	s_mov_b32 m0, s47
	s_nop 0
	global_load_lds_dwordx4 v[146:147], off
	s_waitcnt vmcnt(8)
	s_waitcnt lgkmcnt(0)
	s_barrier
	s_setprio 1
	s_waitcnt lgkmcnt(0)
	v_mfma_f32_16x16x32_bf16 v[60:63], v[162:165], v[194:197], v[60:63]
	v_mfma_f32_16x16x32_bf16 v[56:59], v[170:173], v[194:197], v[56:59]
	v_mfma_f32_16x16x32_bf16 v[44:47], v[162:165], v[202:205], v[44:47]
	v_mfma_f32_16x16x32_bf16 v[40:43], v[170:173], v[202:205], v[40:43]
	v_mfma_f32_16x16x32_bf16 v[28:31], v[162:165], v[210:213], v[28:31]
	v_mfma_f32_16x16x32_bf16 v[24:27], v[170:173], v[210:213], v[24:27]
	v_mfma_f32_16x16x32_bf16 v[12:15], v[162:165], v[218:221], v[12:15]
	v_mfma_f32_16x16x32_bf16 v[8:11], v[170:173], v[218:221], v[8:11]
	v_mfma_f32_16x16x32_bf16 v[60:63], v[166:169], v[198:201], v[60:63]
	v_mfma_f32_16x16x32_bf16 v[56:59], v[174:177], v[198:201], v[56:59]
	v_mfma_f32_16x16x32_bf16 v[44:47], v[166:169], v[206:209], v[44:47]
	v_mfma_f32_16x16x32_bf16 v[40:43], v[174:177], v[206:209], v[40:43]
	v_mfma_f32_16x16x32_bf16 v[28:31], v[166:169], v[214:217], v[28:31]
	v_mfma_f32_16x16x32_bf16 v[24:27], v[174:177], v[214:217], v[24:27]
	v_mfma_f32_16x16x32_bf16 v[12:15], v[166:169], v[222:225], v[12:15]
	v_mfma_f32_16x16x32_bf16 v[8:11], v[174:177], v[222:225], v[8:11]
	v_mfma_f32_16x16x32_bf16 v[52:55], v[178:181], v[194:197], v[52:55]
	v_mfma_f32_16x16x32_bf16 v[48:51], v[186:189], v[194:197], v[48:51]
	v_mfma_f32_16x16x32_bf16 v[36:39], v[178:181], v[202:205], v[36:39]
	v_mfma_f32_16x16x32_bf16 v[32:35], v[186:189], v[202:205], v[32:35]
	v_mfma_f32_16x16x32_bf16 v[20:23], v[178:181], v[210:213], v[20:23]
	v_mfma_f32_16x16x32_bf16 v[16:19], v[186:189], v[210:213], v[16:19]
	v_mfma_f32_16x16x32_bf16 v[4:7], v[178:181], v[218:221], v[4:7]
	v_mfma_f32_16x16x32_bf16 v[0:3], v[186:189], v[218:221], v[0:3]
	v_mfma_f32_16x16x32_bf16 v[52:55], v[182:185], v[198:201], v[52:55]
	v_mfma_f32_16x16x32_bf16 v[48:51], v[190:193], v[198:201], v[48:51]
	v_mfma_f32_16x16x32_bf16 v[36:39], v[182:185], v[206:209], v[36:39]
	v_mfma_f32_16x16x32_bf16 v[32:35], v[190:193], v[206:209], v[32:35]
	v_mfma_f32_16x16x32_bf16 v[20:23], v[182:185], v[214:217], v[20:23]
	v_mfma_f32_16x16x32_bf16 v[16:19], v[190:193], v[214:217], v[16:19]
	v_mfma_f32_16x16x32_bf16 v[4:7], v[182:185], v[222:225], v[4:7]
	v_mfma_f32_16x16x32_bf16 v[0:3], v[190:193], v[222:225], v[0:3]
	s_add_u32 s37, s37, 0x100
	s_addc_u32 s42, s42, 0
	s_cmp_ge_u32 s68, s33
	s_mov_b64 s[52:53], s[54:55]
	s_mov_b32 s56, s68
	s_setprio 0
	s_barrier
	s_cbranch_scc0 .LBB0_1735
	s_xor_b64 s[50:51], s[50:51], -1
	s_and_b64 vcc, exec, s[24:25]
	s_cbranch_vccz .LBB0_1757
